# v27 plus non-temporal hint on bf16-output GEMM epilogue stores (mixer input projections and small projections)
# speedup vs baseline: 1.0030x; 1.0030x over previous
; #define LAS __attribute__((address_space(3)))
; DEVI unsigned pk_bf16(float lo, float hi) { unsigned r; asm("v_cvt_pk_bf16_f32 %0, %1, %2" : "=v"(r) : "v"(lo), "v"(hi)); return r; }
; DEVI float row_rstd(const LAS float* rsl, int r) { return rsqrtf((rsl[r] + rsl[256 + r]) * (1.0f / DM) + 1e-6f); }
;     DEVI void operator()(const f32x4 (&acc)[2][2][4][2], const Unit& u, int wr, int wc, int fr, int fq, const LAS float* rsl) const {
;         bf16_t* const O = O_; const int ldc = ldc_; const float* const rs = rs_; const int rsn = rsn_;
;         const int row0 = u.pm * BM + wr * 64 + fr, col0 = u.pn * BM + wc * 32 + 8 * fq;
; #pragma unroll
;         for (int ai = 0; ai < 2; ++ai)
; #pragma unroll
;             for (int m = 0; m < 4; ++m) { bf16_t* rowp = O + (size_t)(row0 + ai * HALF + m * 16) * ldc + col0;
;                 const float sc = rs ? row_rstd(rsl, wr * 64 + fr + ai * HALF + m * 16) : 1.0f;
; #pragma unroll
;                 for (int bj = 0; bj < 2; ++bj) { const f32x4 v0 = acc[ai][bj][m][0] * sc, v1 = acc[ai][bj][m][1] * sc;
;                     u32x4 w; w.x = pk_bf16(v0[0], v0[1]); w.y = pk_bf16(v0[2], v0[3]); w.z = pk_bf16(v1[0], v1[1]); w.w = pk_bf16(v1[2], v1[3]);
;                     *(u32x4*)(rowp + bj * HALF) = w; } }
;     }
.LBB0_523:
	v_lshl_or_b32 v144, s74, 8, v152
	v_lshl_add_u32 v159, s75, 8, v149
	v_ashrrev_i32_e32 v145, 31, v144
	v_lshl_add_u64 v[144:145], v[144:145], 1, s[64:65]
	v_mad_i64_i32 v[162:163], s[14:15], v159, s70, 0
	v_lshl_add_u64 v[162:163], v[162:163], 1, v[144:145]
	v_pk_mul_f32 v[126:127], v[126:127], v[148:149] op_sel_hi:[1,0]
	v_pk_mul_f32 v[124:125], v[124:125], v[148:149] op_sel_hi:[1,0]
	v_pk_mul_f32 v[164:165], v[122:123], v[148:149] op_sel_hi:[1,0]
	v_pk_mul_f32 v[122:123], v[120:121], v[148:149] op_sel_hi:[1,0]
	v_cvt_pk_bf16_f32 v120, v124, v125
	v_cvt_pk_bf16_f32 v121, v126, v127
	v_pk_mul_f32 v[116:117], v[116:117], v[148:149] op_sel_hi:[1,0]
	v_cvt_pk_bf16_f32 v122, v122, v123
	v_cvt_pk_bf16_f32 v123, v164, v165
	global_store_dwordx4 v[162:163], v[120:123], off nt
	v_pk_mul_f32 v[118:119], v[118:119], v[148:149] op_sel_hi:[1,0]
	s_and_b64 vcc, exec, s[40:41]
	v_pk_mul_f32 v[120:121], v[114:115], v[148:149] op_sel_hi:[1,0]
	v_pk_mul_f32 v[114:115], v[112:113], v[148:149] op_sel_hi:[1,0]
	v_cvt_pk_bf16_f32 v112, v116, v117
	v_cvt_pk_bf16_f32 v113, v118, v119
	s_nop 0
	v_cvt_pk_bf16_f32 v114, v114, v115
	v_cvt_pk_bf16_f32 v115, v120, v121
	global_store_dwordx4 v[162:163], v[112:115], off offset:256 nt
	s_nop 1
	v_add_u32_e32 v112, 64, v160
	s_cbranch_vccnz .LBB0_525
	ds_read2st64_b32 v[114:115], v112 offset1:4
	s_waitcnt lgkmcnt(0)
	v_add_f32_e32 v113, v114, v115
	v_fmamk_f32 v113, v113, 0x3a000000, v158
	v_mul_f32_e32 v114, 0x4b800000, v113
	v_cmp_gt_f32_e32 vcc, s51, v113
	s_nop 1
	v_cndmask_b32_e32 v113, v113, v114, vcc
	v_rsq_f32_e32 v113, v113
	s_nop 0
	v_mul_f32_e32 v114, 0x45800000, v113
	v_cndmask_b32_e32 v146, v113, v114, vcc
.LBB0_525:
	v_or_b32_e32 v113, 16, v159
	v_mad_i64_i32 v[114:115], s[14:15], v113, s70, 0
	v_lshl_add_u64 v[114:115], v[114:115], 1, v[144:145]
	v_pk_mul_f32 v[110:111], v[110:111], v[146:147] op_sel_hi:[1,0]
	v_pk_mul_f32 v[108:109], v[108:109], v[146:147] op_sel_hi:[1,0]
	v_pk_mul_f32 v[116:117], v[106:107], v[146:147] op_sel_hi:[1,0]
	v_pk_mul_f32 v[106:107], v[104:105], v[146:147] op_sel_hi:[1,0]
	v_cvt_pk_bf16_f32 v104, v108, v109
	v_cvt_pk_bf16_f32 v105, v110, v111
	v_pk_mul_f32 v[102:103], v[102:103], v[146:147] op_sel_hi:[1,0]
	v_cvt_pk_bf16_f32 v106, v106, v107
	v_cvt_pk_bf16_f32 v107, v116, v117
	global_store_dwordx4 v[114:115], v[104:107], off nt
	v_pk_mul_f32 v[100:101], v[100:101], v[146:147] op_sel_hi:[1,0]
	s_and_b64 vcc, exec, s[40:41]
	v_pk_mul_f32 v[104:105], v[98:99], v[146:147] op_sel_hi:[1,0]
	v_pk_mul_f32 v[98:99], v[96:97], v[146:147] op_sel_hi:[1,0]
	v_cvt_pk_bf16_f32 v96, v100, v101
	v_cvt_pk_bf16_f32 v97, v102, v103
	s_nop 0
	v_cvt_pk_bf16_f32 v98, v98, v99
	v_cvt_pk_bf16_f32 v99, v104, v105
	global_store_dwordx4 v[114:115], v[96:99], off offset:256 nt
	s_nop 1
	v_mov_b32_e32 v96, 1.0
	v_add_u32_e32 v97, 0x80, v160
	v_mov_b32_e32 v98, 1.0
	s_cbranch_vccnz .LBB0_527
	ds_read2st64_b32 v[98:99], v97 offset1:4
	s_waitcnt lgkmcnt(0)
	v_add_f32_e32 v98, v98, v99
	v_fmamk_f32 v98, v98, 0x3a000000, v158
	v_mul_f32_e32 v99, 0x4b800000, v98
	v_cmp_gt_f32_e32 vcc, s51, v98
	s_nop 1
	v_cndmask_b32_e32 v98, v98, v99, vcc
	v_rsq_f32_e32 v98, v98
	s_nop 0
	v_mul_f32_e32 v99, 0x45800000, v98
	v_cndmask_b32_e32 v98, v98, v99, vcc
.LBB0_527:
	v_or_b32_e32 v99, 32, v159
	v_mad_i64_i32 v[100:101], s[14:15], v99, s70, 0
	v_lshl_add_u64 v[100:101], v[100:101], 1, v[144:145]
	v_pk_mul_f32 v[94:95], v[94:95], v[98:99] op_sel_hi:[1,0]
	v_pk_mul_f32 v[92:93], v[92:93], v[98:99] op_sel_hi:[1,0]
	v_pk_mul_f32 v[102:103], v[90:91], v[98:99] op_sel_hi:[1,0]
	v_pk_mul_f32 v[90:91], v[88:89], v[98:99] op_sel_hi:[1,0]
	v_cvt_pk_bf16_f32 v88, v92, v93
	v_cvt_pk_bf16_f32 v89, v94, v95
	v_pk_mul_f32 v[84:85], v[84:85], v[98:99] op_sel_hi:[1,0]
	v_cvt_pk_bf16_f32 v90, v90, v91
	v_cvt_pk_bf16_f32 v91, v102, v103
	global_store_dwordx4 v[100:101], v[88:91], off nt
	v_pk_mul_f32 v[86:87], v[86:87], v[98:99] op_sel_hi:[1,0]
	s_and_b64 vcc, exec, s[40:41]
	v_pk_mul_f32 v[88:89], v[82:83], v[98:99] op_sel_hi:[1,0]
	v_pk_mul_f32 v[82:83], v[80:81], v[98:99] op_sel_hi:[1,0]
	v_cvt_pk_bf16_f32 v80, v84, v85
	v_cvt_pk_bf16_f32 v81, v86, v87
	s_nop 0
	v_cvt_pk_bf16_f32 v82, v82, v83
	v_cvt_pk_bf16_f32 v83, v88, v89
	global_store_dwordx4 v[100:101], v[80:83], off offset:256 nt
	s_nop 1
	v_add_u32_e32 v80, 0xc0, v160
	s_cbranch_vccnz .LBB0_529
	ds_read2st64_b32 v[82:83], v80 offset1:4
	s_waitcnt lgkmcnt(0)
	v_add_f32_e32 v81, v82, v83
	v_fmamk_f32 v81, v81, 0x3a000000, v158
	v_mul_f32_e32 v82, 0x4b800000, v81
	v_cmp_gt_f32_e32 vcc, s51, v81
	s_nop 1
	v_cndmask_b32_e32 v81, v81, v82, vcc
	v_rsq_f32_e32 v81, v81
	s_nop 0
	v_mul_f32_e32 v82, 0x45800000, v81
	v_cndmask_b32_e32 v96, v81, v82, vcc
.LBB0_529:
	v_or_b32_e32 v81, 48, v159
	v_mad_i64_i32 v[82:83], s[14:15], v81, s70, 0
	v_lshl_add_u64 v[82:83], v[82:83], 1, v[144:145]
	v_pk_mul_f32 v[78:79], v[78:79], v[96:97] op_sel_hi:[1,0]
	v_pk_mul_f32 v[76:77], v[76:77], v[96:97] op_sel_hi:[1,0]
	v_pk_mul_f32 v[84:85], v[74:75], v[96:97] op_sel_hi:[1,0]
	v_pk_mul_f32 v[74:75], v[72:73], v[96:97] op_sel_hi:[1,0]
	v_cvt_pk_bf16_f32 v72, v76, v77
	v_cvt_pk_bf16_f32 v73, v78, v79
	v_pk_mul_f32 v[68:69], v[68:69], v[96:97] op_sel_hi:[1,0]
	v_cvt_pk_bf16_f32 v74, v74, v75
	v_cvt_pk_bf16_f32 v75, v84, v85
	global_store_dwordx4 v[82:83], v[72:75], off nt
	v_pk_mul_f32 v[70:71], v[70:71], v[96:97] op_sel_hi:[1,0]
	s_and_b64 vcc, exec, s[40:41]
	v_pk_mul_f32 v[72:73], v[66:67], v[96:97] op_sel_hi:[1,0]
	v_pk_mul_f32 v[66:67], v[64:65], v[96:97] op_sel_hi:[1,0]
	v_cvt_pk_bf16_f32 v64, v68, v69
	v_cvt_pk_bf16_f32 v65, v70, v71
	s_nop 0
	v_cvt_pk_bf16_f32 v66, v66, v67
	v_cvt_pk_bf16_f32 v67, v72, v73
	global_store_dwordx4 v[82:83], v[64:67], off offset:256 nt
	s_nop 1
	v_mov_b32_e32 v64, 1.0
	v_mov_b32_e32 v66, 1.0
	s_cbranch_vccnz .LBB0_531
	ds_read2st64_b32 v[66:67], v160 offset0:2 offset1:6
	s_waitcnt lgkmcnt(0)
	v_add_f32_e32 v65, v66, v67
	v_fmamk_f32 v65, v65, 0x3a000000, v158
	v_mul_f32_e32 v66, 0x4b800000, v65
	v_cmp_gt_f32_e32 vcc, s51, v65
	s_nop 1
	v_cndmask_b32_e32 v65, v65, v66, vcc
	v_rsq_f32_e32 v65, v65
	s_nop 0
	v_mul_f32_e32 v66, 0x45800000, v65
	v_cndmask_b32_e32 v66, v65, v66, vcc
; #define LAS __attribute__((address_space(3)))
; DEVI unsigned pk_bf16(float lo, float hi) { unsigned r; asm("v_cvt_pk_bf16_f32 %0, %1, %2" : "=v"(r) : "v"(lo), "v"(hi)); return r; }
; DEVI float row_rstd(const LAS float* rsl, int r) { return rsqrtf((rsl[r] + rsl[256 + r]) * (1.0f / DM) + 1e-6f); }
;     DEVI void operator()(const f32x4 (&acc)[2][2][4][2], const Unit& u, int wr, int wc, int fr, int fq, const LAS float* rsl) const {
;         bf16_t* const O = O_; const int ldc = ldc_; const float* const rs = rs_; const int rsn = rsn_;
;         const int row0 = u.pm * BM + wr * 64 + fr, col0 = u.pn * BM + wc * 32 + 8 * fq;
; #pragma unroll
;         for (int ai = 0; ai < 2; ++ai)
; #pragma unroll
;             for (int m = 0; m < 4; ++m) { bf16_t* rowp = O + (size_t)(row0 + ai * HALF + m * 16) * ldc + col0;
;                 const float sc = rs ? row_rstd(rsl, wr * 64 + fr + ai * HALF + m * 16) : 1.0f;
; #pragma unroll
;                 for (int bj = 0; bj < 2; ++bj) { const f32x4 v0 = acc[ai][bj][m][0] * sc, v1 = acc[ai][bj][m][1] * sc;
;                     u32x4 w; w.x = pk_bf16(v0[0], v0[1]); w.y = pk_bf16(v0[2], v0[3]); w.z = pk_bf16(v1[0], v1[1]); w.w = pk_bf16(v1[2], v1[3]);
;                     *(u32x4*)(rowp + bj * HALF) = w; } }
;     }
; template <class Epi>
; DEVI void gemm_phase(LAS unsigned char* lds, const bf16_t* gA, const bf16_t* gBt, const int lda, const int ldb, const int K, const StaticOrder S_, const Epi E) {
;     ...
;         if (!has_next) break;
; #pragma unroll
;         for (int a = 0; a < 2; ++a)
; #pragma unroll
;             for (int b = 0; b < 2; ++b)
; #pragma unroll
;                 for (int m = 0; m < 4; ++m)
; #pragma unroll
;                     for (int n = 0; n < 2; ++n) acc[a][b][m][n] = (f32x4){0.f, 0.f, 0.f, 0.f};
;         cur = nxt; cA = nA; cB = nB; ++ui;
;         rs_prefetch(cur, ui & 1);
.LBB0_531:
	v_add_u32_e32 v65, 0x80, v159
	v_mad_i64_i32 v[68:69], s[14:15], v65, s70, 0
	v_lshl_add_u64 v[68:69], v[68:69], 1, v[144:145]
	v_pk_mul_f32 v[62:63], v[62:63], v[66:67] op_sel_hi:[1,0]
	v_pk_mul_f32 v[60:61], v[60:61], v[66:67] op_sel_hi:[1,0]
	v_pk_mul_f32 v[70:71], v[58:59], v[66:67] op_sel_hi:[1,0]
	v_pk_mul_f32 v[58:59], v[56:57], v[66:67] op_sel_hi:[1,0]
	v_cvt_pk_bf16_f32 v56, v60, v61
	v_cvt_pk_bf16_f32 v57, v62, v63
	s_and_b64 vcc, exec, s[40:41]
	v_cvt_pk_bf16_f32 v58, v58, v59
	v_cvt_pk_bf16_f32 v59, v70, v71
	global_store_dwordx4 v[68:69], v[56:59], off nt
	v_pk_mul_f32 v[54:55], v[54:55], v[66:67] op_sel_hi:[1,0]
	v_pk_mul_f32 v[52:53], v[52:53], v[66:67] op_sel_hi:[1,0]
	v_pk_mul_f32 v[56:57], v[50:51], v[66:67] op_sel_hi:[1,0]
	v_pk_mul_f32 v[50:51], v[48:49], v[66:67] op_sel_hi:[1,0]
	v_cvt_pk_bf16_f32 v48, v52, v53
	v_cvt_pk_bf16_f32 v49, v54, v55
	s_nop 0
	v_cvt_pk_bf16_f32 v50, v50, v51
	v_cvt_pk_bf16_f32 v51, v56, v57
	global_store_dwordx4 v[68:69], v[48:51], off offset:256 nt
	s_cbranch_vccnz .LBB0_533
	ds_read2st64_b32 v[48:49], v112 offset0:2 offset1:6
	s_waitcnt lgkmcnt(0)
	v_add_f32_e32 v48, v48, v49
	v_fmamk_f32 v48, v48, 0x3a000000, v158
	v_mul_f32_e32 v49, 0x4b800000, v48
	v_cmp_gt_f32_e32 vcc, s51, v48
	s_nop 1
	v_cndmask_b32_e32 v48, v48, v49, vcc
	v_rsq_f32_e32 v48, v48
	s_nop 0
	v_mul_f32_e32 v49, 0x45800000, v48
	v_cndmask_b32_e32 v64, v48, v49, vcc
.LBB0_533:
	s_nop 0
	v_add_u32_e32 v48, 0x90, v159
	v_mad_i64_i32 v[48:49], s[14:15], v48, s70, 0
	v_lshl_add_u64 v[48:49], v[48:49], 1, v[144:145]
	v_pk_mul_f32 v[46:47], v[46:47], v[64:65] op_sel_hi:[1,0]
	v_pk_mul_f32 v[44:45], v[44:45], v[64:65] op_sel_hi:[1,0]
	v_pk_mul_f32 v[50:51], v[42:43], v[64:65] op_sel_hi:[1,0]
	v_pk_mul_f32 v[42:43], v[40:41], v[64:65] op_sel_hi:[1,0]
	v_cvt_pk_bf16_f32 v40, v44, v45
	v_cvt_pk_bf16_f32 v41, v46, v47
	v_pk_mul_f32 v[36:37], v[36:37], v[64:65] op_sel_hi:[1,0]
	v_cvt_pk_bf16_f32 v42, v42, v43
	v_cvt_pk_bf16_f32 v43, v50, v51
	global_store_dwordx4 v[48:49], v[40:43], off nt
	v_pk_mul_f32 v[38:39], v[38:39], v[64:65] op_sel_hi:[1,0]
	s_and_b64 vcc, exec, s[40:41]
	v_pk_mul_f32 v[40:41], v[34:35], v[64:65] op_sel_hi:[1,0]
	v_pk_mul_f32 v[34:35], v[32:33], v[64:65] op_sel_hi:[1,0]
	v_cvt_pk_bf16_f32 v32, v36, v37
	v_cvt_pk_bf16_f32 v33, v38, v39
	s_nop 0
	v_cvt_pk_bf16_f32 v34, v34, v35
	v_cvt_pk_bf16_f32 v35, v40, v41
	global_store_dwordx4 v[48:49], v[32:35], off offset:256 nt
	s_nop 1
	v_mov_b32_e32 v32, 1.0
	v_mov_b32_e32 v34, 1.0
	s_cbranch_vccnz .LBB0_535
	ds_read2st64_b32 v[34:35], v97 offset0:2 offset1:6
	s_waitcnt lgkmcnt(0)
	v_add_f32_e32 v33, v34, v35
	v_fmamk_f32 v33, v33, 0x3a000000, v158
	v_mul_f32_e32 v34, 0x4b800000, v33
	v_cmp_gt_f32_e32 vcc, s51, v33
	s_nop 1
	v_cndmask_b32_e32 v33, v33, v34, vcc
	v_rsq_f32_e32 v33, v33
	s_nop 0
	v_mul_f32_e32 v34, 0x45800000, v33
	v_cndmask_b32_e32 v34, v33, v34, vcc
.LBB0_535:
	v_add_u32_e32 v33, 0xa0, v159
	v_mad_i64_i32 v[36:37], s[14:15], v33, s70, 0
	v_lshl_add_u64 v[36:37], v[36:37], 1, v[144:145]
	v_pk_mul_f32 v[30:31], v[30:31], v[34:35] op_sel_hi:[1,0]
	v_pk_mul_f32 v[28:29], v[28:29], v[34:35] op_sel_hi:[1,0]
	v_pk_mul_f32 v[38:39], v[26:27], v[34:35] op_sel_hi:[1,0]
	v_pk_mul_f32 v[26:27], v[24:25], v[34:35] op_sel_hi:[1,0]
	v_cvt_pk_bf16_f32 v24, v28, v29
	v_cvt_pk_bf16_f32 v25, v30, v31
	s_and_b64 vcc, exec, s[40:41]
	v_cvt_pk_bf16_f32 v26, v26, v27
	v_cvt_pk_bf16_f32 v27, v38, v39
	global_store_dwordx4 v[36:37], v[24:27], off nt
	v_pk_mul_f32 v[22:23], v[22:23], v[34:35] op_sel_hi:[1,0]
	v_pk_mul_f32 v[20:21], v[20:21], v[34:35] op_sel_hi:[1,0]
	v_pk_mul_f32 v[24:25], v[18:19], v[34:35] op_sel_hi:[1,0]
	v_pk_mul_f32 v[18:19], v[16:17], v[34:35] op_sel_hi:[1,0]
	v_cvt_pk_bf16_f32 v16, v20, v21
	v_cvt_pk_bf16_f32 v17, v22, v23
	s_nop 0
	v_cvt_pk_bf16_f32 v18, v18, v19
	v_cvt_pk_bf16_f32 v19, v24, v25
	global_store_dwordx4 v[36:37], v[16:19], off offset:256 nt
	s_cbranch_vccnz .LBB0_537
	ds_read2st64_b32 v[16:17], v80 offset0:2 offset1:6
	s_waitcnt lgkmcnt(0)
	v_add_f32_e32 v16, v16, v17
	v_fmamk_f32 v16, v16, 0x3a000000, v158
	v_mul_f32_e32 v17, 0x4b800000, v16
	v_cmp_gt_f32_e32 vcc, s51, v16
	s_nop 1
	v_cndmask_b32_e32 v16, v16, v17, vcc
	v_rsq_f32_e32 v16, v16
	s_nop 0
	v_mul_f32_e32 v17, 0x45800000, v16
	v_cndmask_b32_e32 v32, v16, v17, vcc
.LBB0_537:
	s_nop 0
	v_add_u32_e32 v16, 0xb0, v159
	v_mad_i64_i32 v[16:17], s[14:15], v16, s70, 0
	v_lshl_add_u64 v[16:17], v[16:17], 1, v[144:145]
	v_pk_mul_f32 v[14:15], v[14:15], v[32:33] op_sel_hi:[1,0]
	v_pk_mul_f32 v[12:13], v[12:13], v[32:33] op_sel_hi:[1,0]
	v_pk_mul_f32 v[18:19], v[10:11], v[32:33] op_sel_hi:[1,0]
	v_pk_mul_f32 v[10:11], v[8:9], v[32:33] op_sel_hi:[1,0]
	v_cvt_pk_bf16_f32 v8, v12, v13
	v_cvt_pk_bf16_f32 v9, v14, v15
	s_and_b64 vcc, exec, s[38:39]
	v_cvt_pk_bf16_f32 v10, v10, v11
	v_cvt_pk_bf16_f32 v11, v18, v19
	global_store_dwordx4 v[16:17], v[8:11], off nt
	s_mov_b64 s[14:15], -1
	v_pk_mul_f32 v[6:7], v[6:7], v[32:33] op_sel_hi:[1,0]
	v_pk_mul_f32 v[8:9], v[2:3], v[32:33] op_sel_hi:[1,0]
	v_pk_mul_f32 v[2:3], v[0:1], v[32:33] op_sel_hi:[1,0]
	v_pk_mul_f32 v[4:5], v[4:5], v[32:33] op_sel_hi:[1,0]
	v_cvt_pk_bf16_f32 v1, v6, v7
	v_cvt_pk_bf16_f32 v2, v2, v3
	v_cvt_pk_bf16_f32 v3, v8, v9
	s_nop 0
	v_cvt_pk_bf16_f32 v0, v4, v5
	global_store_dwordx4 v[16:17], v[0:3], off offset:256 nt
	s_cbranch_vccnz .LBB0_510
	s_and_b64 vcc, exec, s[12:13]
	s_cbranch_vccz .LBB0_509
	v_lshl_or_b32 v0, s73, 8, v147
	v_ashrrev_i32_e32 v1, 31, v0
	v_lshlrev_b64 v[0:1], 7, v[0:1]
	v_lshl_add_u64 v[0:1], v[136:137], 0, v[0:1]
	s_and_b64 vcc, exec, s[42:43]
	s_cbranch_vccz .LBB0_543
	v_mov_b32_e32 v2, 0
	s_and_saveexec_b64 s[14:15], s[36:37]
	s_cbranch_execz .LBB0_542
	global_load_dword v2, v[0:1], off

; #define LAS __attribute__((address_space(3)))
; DEVI unsigned pk_bf16(float lo, float hi) { unsigned r; asm("v_cvt_pk_bf16_f32 %0, %1, %2" : "=v"(r) : "v"(lo), "v"(hi)); return r; }
; DEVI float row_rstd(const LAS float* rsl, int r) { return rsqrtf((rsl[r] + rsl[256 + r]) * (1.0f / DM) + 1e-6f); }
;     DEVI void operator()(const f32x4 (&acc)[2][2][4][2], const Unit& u, int wr, int wc, int fr, int fq, const LAS float* rsl) const {
;         bf16_t* const O = O_; const int ldc = ldc_; const float* const rs = rs_; const int rsn = rsn_;
;         const int row0 = u.pm * BM + wr * 64 + fr, col0 = u.pn * BM + wc * 32 + 8 * fq;
; #pragma unroll
;         for (int ai = 0; ai < 2; ++ai)
; #pragma unroll
;             for (int m = 0; m < 4; ++m) { bf16_t* rowp = O + (size_t)(row0 + ai * HALF + m * 16) * ldc + col0;
;                 const float sc = rs ? row_rstd(rsl, wr * 64 + fr + ai * HALF + m * 16) : 1.0f;
; #pragma unroll
;                 for (int bj = 0; bj < 2; ++bj) { const f32x4 v0 = acc[ai][bj][m][0] * sc, v1 = acc[ai][bj][m][1] * sc;
;                     u32x4 w; w.x = pk_bf16(v0[0], v0[1]); w.y = pk_bf16(v0[2], v0[3]); w.z = pk_bf16(v1[0], v1[1]); w.w = pk_bf16(v1[2], v1[3]);
;                     *(u32x4*)(rowp + bj * HALF) = w; } }
;     }
.LBB0_748:
	v_lshl_or_b32 v144, s74, 8, v152
	v_readlane_b32 s14, v239, 16
	v_readlane_b32 s88, v239, 18
	v_lshl_add_u32 v159, s75, 8, v149
	v_ashrrev_i32_e32 v145, 31, v144
	v_readlane_b32 s15, v239, 17
	v_readlane_b32 s90, v239, 20
	v_pk_mul_f32 v[126:127], v[126:127], v[148:149] op_sel_hi:[1,0]
	v_lshl_add_u64 v[144:145], v[144:145], 1, s[14:15]
	v_mad_i64_i32 v[162:163], s[14:15], v159, s90, 0
	v_lshl_add_u64 v[162:163], v[162:163], 1, v[144:145]
	v_pk_mul_f32 v[124:125], v[124:125], v[148:149] op_sel_hi:[1,0]
	v_pk_mul_f32 v[164:165], v[122:123], v[148:149] op_sel_hi:[1,0]
	v_pk_mul_f32 v[122:123], v[120:121], v[148:149] op_sel_hi:[1,0]
	v_cvt_pk_bf16_f32 v120, v124, v125
	v_cvt_pk_bf16_f32 v121, v126, v127
	v_pk_mul_f32 v[116:117], v[116:117], v[148:149] op_sel_hi:[1,0]
	v_cvt_pk_bf16_f32 v122, v122, v123
	v_cvt_pk_bf16_f32 v123, v164, v165
	global_store_dwordx4 v[162:163], v[120:123], off nt
	v_pk_mul_f32 v[118:119], v[118:119], v[148:149] op_sel_hi:[1,0]
	s_and_b64 vcc, exec, s[40:41]
	v_pk_mul_f32 v[120:121], v[114:115], v[148:149] op_sel_hi:[1,0]
	v_pk_mul_f32 v[114:115], v[112:113], v[148:149] op_sel_hi:[1,0]
	v_cvt_pk_bf16_f32 v112, v116, v117
	v_cvt_pk_bf16_f32 v113, v118, v119
	v_readlane_b32 s89, v239, 19
	v_cvt_pk_bf16_f32 v114, v114, v115
	v_cvt_pk_bf16_f32 v115, v120, v121
	global_store_dwordx4 v[162:163], v[112:115], off offset:256 nt
	v_readlane_b32 s91, v239, 21
	s_nop 0
	v_add_u32_e32 v112, 64, v160
	s_cbranch_vccnz .LBB0_750
	ds_read2st64_b32 v[114:115], v112 offset1:4
	s_waitcnt lgkmcnt(0)
	v_add_f32_e32 v113, v114, v115
	v_fmamk_f32 v113, v113, 0x3a000000, v158
	v_mul_f32_e32 v114, 0x4b800000, v113
	v_cmp_gt_f32_e32 vcc, s51, v113
	s_nop 1
	v_cndmask_b32_e32 v113, v113, v114, vcc
	v_rsq_f32_e32 v113, v113
	s_nop 0
	v_mul_f32_e32 v114, 0x45800000, v113
	v_cndmask_b32_e32 v146, v113, v114, vcc
.LBB0_750:
	v_readlane_b32 s88, v239, 18
	v_or_b32_e32 v113, 16, v159
	v_readlane_b32 s90, v239, 20
	v_pk_mul_f32 v[110:111], v[110:111], v[146:147] op_sel_hi:[1,0]
	v_pk_mul_f32 v[108:109], v[108:109], v[146:147] op_sel_hi:[1,0]
	v_mad_i64_i32 v[114:115], s[14:15], v113, s90, 0
	v_lshl_add_u64 v[114:115], v[114:115], 1, v[144:145]
	v_pk_mul_f32 v[116:117], v[106:107], v[146:147] op_sel_hi:[1,0]
	v_pk_mul_f32 v[106:107], v[104:105], v[146:147] op_sel_hi:[1,0]
	v_cvt_pk_bf16_f32 v104, v108, v109
	v_cvt_pk_bf16_f32 v105, v110, v111
	v_pk_mul_f32 v[102:103], v[102:103], v[146:147] op_sel_hi:[1,0]
	v_cvt_pk_bf16_f32 v106, v106, v107
	v_cvt_pk_bf16_f32 v107, v116, v117
	global_store_dwordx4 v[114:115], v[104:107], off nt
	v_pk_mul_f32 v[100:101], v[100:101], v[146:147] op_sel_hi:[1,0]
	s_and_b64 vcc, exec, s[40:41]
	v_pk_mul_f32 v[104:105], v[98:99], v[146:147] op_sel_hi:[1,0]
	v_pk_mul_f32 v[98:99], v[96:97], v[146:147] op_sel_hi:[1,0]
	v_cvt_pk_bf16_f32 v96, v100, v101
	v_cvt_pk_bf16_f32 v97, v102, v103
	v_readlane_b32 s89, v239, 19
	v_cvt_pk_bf16_f32 v98, v98, v99
	v_cvt_pk_bf16_f32 v99, v104, v105
	global_store_dwordx4 v[114:115], v[96:99], off offset:256 nt
	v_readlane_b32 s91, v239, 21
	s_nop 0
	v_mov_b32_e32 v96, 1.0
	v_add_u32_e32 v97, 0x80, v160
	v_mov_b32_e32 v98, 1.0
	s_cbranch_vccnz .LBB0_752
	ds_read2st64_b32 v[98:99], v97 offset1:4
	s_waitcnt lgkmcnt(0)
	v_add_f32_e32 v98, v98, v99
	v_fmamk_f32 v98, v98, 0x3a000000, v158
	v_mul_f32_e32 v99, 0x4b800000, v98
	v_cmp_gt_f32_e32 vcc, s51, v98
	s_nop 1
	v_cndmask_b32_e32 v98, v98, v99, vcc
	v_rsq_f32_e32 v98, v98
	s_nop 0
	v_mul_f32_e32 v99, 0x45800000, v98
	v_cndmask_b32_e32 v98, v98, v99, vcc
.LBB0_752:
	v_readlane_b32 s88, v239, 18
	v_or_b32_e32 v99, 32, v159
	v_readlane_b32 s90, v239, 20
	v_pk_mul_f32 v[94:95], v[94:95], v[98:99] op_sel_hi:[1,0]
	v_pk_mul_f32 v[92:93], v[92:93], v[98:99] op_sel_hi:[1,0]
	v_mad_i64_i32 v[100:101], s[14:15], v99, s90, 0
	v_lshl_add_u64 v[100:101], v[100:101], 1, v[144:145]
	v_pk_mul_f32 v[102:103], v[90:91], v[98:99] op_sel_hi:[1,0]
	v_pk_mul_f32 v[90:91], v[88:89], v[98:99] op_sel_hi:[1,0]
	v_cvt_pk_bf16_f32 v88, v92, v93
	v_cvt_pk_bf16_f32 v89, v94, v95
	v_pk_mul_f32 v[84:85], v[84:85], v[98:99] op_sel_hi:[1,0]
	v_cvt_pk_bf16_f32 v90, v90, v91
	v_cvt_pk_bf16_f32 v91, v102, v103
	global_store_dwordx4 v[100:101], v[88:91], off nt
	v_pk_mul_f32 v[86:87], v[86:87], v[98:99] op_sel_hi:[1,0]
	s_and_b64 vcc, exec, s[40:41]
	v_pk_mul_f32 v[88:89], v[82:83], v[98:99] op_sel_hi:[1,0]
	v_pk_mul_f32 v[82:83], v[80:81], v[98:99] op_sel_hi:[1,0]
	v_cvt_pk_bf16_f32 v80, v84, v85
	v_cvt_pk_bf16_f32 v81, v86, v87
	v_readlane_b32 s89, v239, 19
	v_cvt_pk_bf16_f32 v82, v82, v83
	v_cvt_pk_bf16_f32 v83, v88, v89
	global_store_dwordx4 v[100:101], v[80:83], off offset:256 nt
	v_readlane_b32 s91, v239, 21
	s_nop 0
	v_add_u32_e32 v80, 0xc0, v160
	s_cbranch_vccnz .LBB0_754
	ds_read2st64_b32 v[82:83], v80 offset1:4
	s_waitcnt lgkmcnt(0)
	v_add_f32_e32 v81, v82, v83
	v_fmamk_f32 v81, v81, 0x3a000000, v158
	v_mul_f32_e32 v82, 0x4b800000, v81
	v_cmp_gt_f32_e32 vcc, s51, v81
	s_nop 1
	v_cndmask_b32_e32 v81, v81, v82, vcc
	v_rsq_f32_e32 v81, v81
	s_nop 0
	v_mul_f32_e32 v82, 0x45800000, v81
	v_cndmask_b32_e32 v96, v81, v82, vcc
; #define LAS __attribute__((address_space(3)))
; DEVI unsigned pk_bf16(float lo, float hi) { unsigned r; asm("v_cvt_pk_bf16_f32 %0, %1, %2" : "=v"(r) : "v"(lo), "v"(hi)); return r; }
; DEVI float row_rstd(const LAS float* rsl, int r) { return rsqrtf((rsl[r] + rsl[256 + r]) * (1.0f / DM) + 1e-6f); }
;     DEVI void operator()(const f32x4 (&acc)[2][2][4][2], const Unit& u, int wr, int wc, int fr, int fq, const LAS float* rsl) const {
;         bf16_t* const O = O_; const int ldc = ldc_; const float* const rs = rs_; const int rsn = rsn_;
;         const int row0 = u.pm * BM + wr * 64 + fr, col0 = u.pn * BM + wc * 32 + 8 * fq;
; #pragma unroll
;         for (int ai = 0; ai < 2; ++ai)
; #pragma unroll
;             for (int m = 0; m < 4; ++m) { bf16_t* rowp = O + (size_t)(row0 + ai * HALF + m * 16) * ldc + col0;
;                 const float sc = rs ? row_rstd(rsl, wr * 64 + fr + ai * HALF + m * 16) : 1.0f;
; #pragma unroll
;                 for (int bj = 0; bj < 2; ++bj) { const f32x4 v0 = acc[ai][bj][m][0] * sc, v1 = acc[ai][bj][m][1] * sc;
;                     u32x4 w; w.x = pk_bf16(v0[0], v0[1]); w.y = pk_bf16(v0[2], v0[3]); w.z = pk_bf16(v1[0], v1[1]); w.w = pk_bf16(v1[2], v1[3]);
;                     *(u32x4*)(rowp + bj * HALF) = w; } }
;     }
.LBB0_754:
	v_readlane_b32 s88, v239, 18
	v_or_b32_e32 v81, 48, v159
	v_readlane_b32 s90, v239, 20
	v_pk_mul_f32 v[78:79], v[78:79], v[96:97] op_sel_hi:[1,0]
	v_pk_mul_f32 v[76:77], v[76:77], v[96:97] op_sel_hi:[1,0]
	v_mad_i64_i32 v[82:83], s[14:15], v81, s90, 0
	v_lshl_add_u64 v[82:83], v[82:83], 1, v[144:145]
	v_pk_mul_f32 v[84:85], v[74:75], v[96:97] op_sel_hi:[1,0]
	v_pk_mul_f32 v[74:75], v[72:73], v[96:97] op_sel_hi:[1,0]
	v_cvt_pk_bf16_f32 v72, v76, v77
	v_cvt_pk_bf16_f32 v73, v78, v79
	v_pk_mul_f32 v[68:69], v[68:69], v[96:97] op_sel_hi:[1,0]
	v_cvt_pk_bf16_f32 v74, v74, v75
	v_cvt_pk_bf16_f32 v75, v84, v85
	global_store_dwordx4 v[82:83], v[72:75], off nt
	v_pk_mul_f32 v[70:71], v[70:71], v[96:97] op_sel_hi:[1,0]
	s_and_b64 vcc, exec, s[40:41]
	v_pk_mul_f32 v[72:73], v[66:67], v[96:97] op_sel_hi:[1,0]
	v_pk_mul_f32 v[66:67], v[64:65], v[96:97] op_sel_hi:[1,0]
	v_cvt_pk_bf16_f32 v64, v68, v69
	v_cvt_pk_bf16_f32 v65, v70, v71
	v_readlane_b32 s89, v239, 19
	v_cvt_pk_bf16_f32 v66, v66, v67
	v_cvt_pk_bf16_f32 v67, v72, v73
	global_store_dwordx4 v[82:83], v[64:67], off offset:256 nt
	v_readlane_b32 s91, v239, 21
	s_nop 0
	v_mov_b32_e32 v64, 1.0
	v_mov_b32_e32 v66, 1.0
	s_cbranch_vccnz .LBB0_756
	ds_read2st64_b32 v[66:67], v160 offset0:2 offset1:6
	s_waitcnt lgkmcnt(0)
	v_add_f32_e32 v65, v66, v67
	v_fmamk_f32 v65, v65, 0x3a000000, v158
	v_mul_f32_e32 v66, 0x4b800000, v65
	v_cmp_gt_f32_e32 vcc, s51, v65
	s_nop 1
	v_cndmask_b32_e32 v65, v65, v66, vcc
	v_rsq_f32_e32 v65, v65
	s_nop 0
	v_mul_f32_e32 v66, 0x45800000, v65
	v_cndmask_b32_e32 v66, v65, v66, vcc
.LBB0_756:
	v_readlane_b32 s88, v239, 18
	v_add_u32_e32 v65, 0x80, v159
	v_readlane_b32 s90, v239, 20
	v_pk_mul_f32 v[62:63], v[62:63], v[66:67] op_sel_hi:[1,0]
	v_pk_mul_f32 v[60:61], v[60:61], v[66:67] op_sel_hi:[1,0]
	v_mad_i64_i32 v[68:69], s[14:15], v65, s90, 0
	v_lshl_add_u64 v[68:69], v[68:69], 1, v[144:145]
	v_pk_mul_f32 v[70:71], v[58:59], v[66:67] op_sel_hi:[1,0]
	v_pk_mul_f32 v[58:59], v[56:57], v[66:67] op_sel_hi:[1,0]
	v_cvt_pk_bf16_f32 v56, v60, v61
	v_cvt_pk_bf16_f32 v57, v62, v63
	s_and_b64 vcc, exec, s[40:41]
	v_cvt_pk_bf16_f32 v58, v58, v59
	v_cvt_pk_bf16_f32 v59, v70, v71
	global_store_dwordx4 v[68:69], v[56:59], off nt
	v_readlane_b32 s89, v239, 19
	v_readlane_b32 s91, v239, 21
	v_pk_mul_f32 v[56:57], v[50:51], v[66:67] op_sel_hi:[1,0]
	v_pk_mul_f32 v[50:51], v[48:49], v[66:67] op_sel_hi:[1,0]
	v_pk_mul_f32 v[54:55], v[54:55], v[66:67] op_sel_hi:[1,0]
	v_pk_mul_f32 v[52:53], v[52:53], v[66:67] op_sel_hi:[1,0]
	v_cvt_pk_bf16_f32 v49, v54, v55
	v_cvt_pk_bf16_f32 v50, v50, v51
	v_cvt_pk_bf16_f32 v51, v56, v57
	s_nop 0
	v_cvt_pk_bf16_f32 v48, v52, v53
	global_store_dwordx4 v[68:69], v[48:51], off offset:256 nt
	s_cbranch_vccnz .LBB0_758
	ds_read2st64_b32 v[48:49], v112 offset0:2 offset1:6
	s_waitcnt lgkmcnt(0)
	v_add_f32_e32 v48, v48, v49
	v_fmamk_f32 v48, v48, 0x3a000000, v158
	v_mul_f32_e32 v49, 0x4b800000, v48
	v_cmp_gt_f32_e32 vcc, s51, v48
	s_nop 1
	v_cndmask_b32_e32 v48, v48, v49, vcc
	v_rsq_f32_e32 v48, v48
	s_nop 0
	v_mul_f32_e32 v49, 0x45800000, v48
	v_cndmask_b32_e32 v64, v48, v49, vcc
; #define LAS __attribute__((address_space(3)))
; DEVI unsigned pk_bf16(float lo, float hi) { unsigned r; asm("v_cvt_pk_bf16_f32 %0, %1, %2" : "=v"(r) : "v"(lo), "v"(hi)); return r; }
; DEVI float row_rstd(const LAS float* rsl, int r) { return rsqrtf((rsl[r] + rsl[256 + r]) * (1.0f / DM) + 1e-6f); }
;     DEVI void operator()(const f32x4 (&acc)[2][2][4][2], const Unit& u, int wr, int wc, int fr, int fq, const LAS float* rsl) const {
;         bf16_t* const O = O_; const int ldc = ldc_; const float* const rs = rs_; const int rsn = rsn_;
;         const int row0 = u.pm * BM + wr * 64 + fr, col0 = u.pn * BM + wc * 32 + 8 * fq;
; #pragma unroll
;         for (int ai = 0; ai < 2; ++ai)
; #pragma unroll
;             for (int m = 0; m < 4; ++m) { bf16_t* rowp = O + (size_t)(row0 + ai * HALF + m * 16) * ldc + col0;
;                 const float sc = rs ? row_rstd(rsl, wr * 64 + fr + ai * HALF + m * 16) : 1.0f;
; #pragma unroll
;                 for (int bj = 0; bj < 2; ++bj) { const f32x4 v0 = acc[ai][bj][m][0] * sc, v1 = acc[ai][bj][m][1] * sc;
;                     u32x4 w; w.x = pk_bf16(v0[0], v0[1]); w.y = pk_bf16(v0[2], v0[3]); w.z = pk_bf16(v1[0], v1[1]); w.w = pk_bf16(v1[2], v1[3]);
;                     *(u32x4*)(rowp + bj * HALF) = w; } }
;     }
; template <class Epi>
; DEVI void gemm_phase(LAS unsigned char* lds, const bf16_t* gA, const bf16_t* gBt, const int lda, const int ldb, const int K, const StaticOrder S_, const Epi E) {
;     ...
;         if (!has_next) break;
; #pragma unroll
;         for (int a = 0; a < 2; ++a)
; #pragma unroll
;             for (int b = 0; b < 2; ++b)
; #pragma unroll
;                 for (int m = 0; m < 4; ++m)
; #pragma unroll
;                     for (int n = 0; n < 2; ++n) acc[a][b][m][n] = (f32x4){0.f, 0.f, 0.f, 0.f};
;         cur = nxt; cA = nA; cB = nB; ++ui;
;         rs_prefetch(cur, ui & 1);
.LBB0_758:
	v_readlane_b32 s88, v239, 18
	v_add_u32_e32 v48, 0x90, v159
	v_readlane_b32 s90, v239, 20
	v_pk_mul_f32 v[46:47], v[46:47], v[64:65] op_sel_hi:[1,0]
	v_pk_mul_f32 v[44:45], v[44:45], v[64:65] op_sel_hi:[1,0]
	v_mad_i64_i32 v[48:49], s[14:15], v48, s90, 0
	v_lshl_add_u64 v[48:49], v[48:49], 1, v[144:145]
	v_pk_mul_f32 v[50:51], v[42:43], v[64:65] op_sel_hi:[1,0]
	v_pk_mul_f32 v[42:43], v[40:41], v[64:65] op_sel_hi:[1,0]
	v_cvt_pk_bf16_f32 v40, v44, v45
	v_cvt_pk_bf16_f32 v41, v46, v47
	v_pk_mul_f32 v[36:37], v[36:37], v[64:65] op_sel_hi:[1,0]
	v_cvt_pk_bf16_f32 v42, v42, v43
	v_cvt_pk_bf16_f32 v43, v50, v51
	global_store_dwordx4 v[48:49], v[40:43], off nt
	v_pk_mul_f32 v[38:39], v[38:39], v[64:65] op_sel_hi:[1,0]
	s_and_b64 vcc, exec, s[40:41]
	v_pk_mul_f32 v[40:41], v[34:35], v[64:65] op_sel_hi:[1,0]
	v_pk_mul_f32 v[34:35], v[32:33], v[64:65] op_sel_hi:[1,0]
	v_cvt_pk_bf16_f32 v32, v36, v37
	v_cvt_pk_bf16_f32 v33, v38, v39
	v_readlane_b32 s89, v239, 19
	v_cvt_pk_bf16_f32 v34, v34, v35
	v_cvt_pk_bf16_f32 v35, v40, v41
	global_store_dwordx4 v[48:49], v[32:35], off offset:256 nt
	v_readlane_b32 s91, v239, 21
	s_nop 0
	v_mov_b32_e32 v32, 1.0
	v_mov_b32_e32 v34, 1.0
	s_cbranch_vccnz .LBB0_760
	ds_read2st64_b32 v[34:35], v97 offset0:2 offset1:6
	s_waitcnt lgkmcnt(0)
	v_add_f32_e32 v33, v34, v35
	v_fmamk_f32 v33, v33, 0x3a000000, v158
	v_mul_f32_e32 v34, 0x4b800000, v33
	v_cmp_gt_f32_e32 vcc, s51, v33
	s_nop 1
	v_cndmask_b32_e32 v33, v33, v34, vcc
	v_rsq_f32_e32 v33, v33
	s_nop 0
	v_mul_f32_e32 v34, 0x45800000, v33
	v_cndmask_b32_e32 v34, v33, v34, vcc
.LBB0_760:
	v_readlane_b32 s88, v239, 18
	v_add_u32_e32 v33, 0xa0, v159
	v_readlane_b32 s90, v239, 20
	v_pk_mul_f32 v[30:31], v[30:31], v[34:35] op_sel_hi:[1,0]
	v_pk_mul_f32 v[28:29], v[28:29], v[34:35] op_sel_hi:[1,0]
	v_mad_i64_i32 v[36:37], s[14:15], v33, s90, 0
	v_lshl_add_u64 v[36:37], v[36:37], 1, v[144:145]
	v_pk_mul_f32 v[38:39], v[26:27], v[34:35] op_sel_hi:[1,0]
	v_pk_mul_f32 v[26:27], v[24:25], v[34:35] op_sel_hi:[1,0]
	v_cvt_pk_bf16_f32 v24, v28, v29
	v_cvt_pk_bf16_f32 v25, v30, v31
	s_and_b64 vcc, exec, s[40:41]
	v_cvt_pk_bf16_f32 v26, v26, v27
	v_cvt_pk_bf16_f32 v27, v38, v39
	global_store_dwordx4 v[36:37], v[24:27], off nt
	v_readlane_b32 s89, v239, 19
	v_readlane_b32 s91, v239, 21
	v_pk_mul_f32 v[24:25], v[18:19], v[34:35] op_sel_hi:[1,0]
	v_pk_mul_f32 v[18:19], v[16:17], v[34:35] op_sel_hi:[1,0]
	v_pk_mul_f32 v[22:23], v[22:23], v[34:35] op_sel_hi:[1,0]
	v_pk_mul_f32 v[20:21], v[20:21], v[34:35] op_sel_hi:[1,0]
	v_cvt_pk_bf16_f32 v17, v22, v23
	v_cvt_pk_bf16_f32 v18, v18, v19
	v_cvt_pk_bf16_f32 v19, v24, v25
	s_nop 0
	v_cvt_pk_bf16_f32 v16, v20, v21
	global_store_dwordx4 v[36:37], v[16:19], off offset:256 nt
	s_cbranch_vccnz .LBB0_762
	ds_read2st64_b32 v[16:17], v80 offset0:2 offset1:6
	s_waitcnt lgkmcnt(0)
	v_add_f32_e32 v16, v16, v17
	v_fmamk_f32 v16, v16, 0x3a000000, v158
	v_mul_f32_e32 v17, 0x4b800000, v16
	v_cmp_gt_f32_e32 vcc, s51, v16
	s_nop 1
	v_cndmask_b32_e32 v16, v16, v17, vcc
	v_rsq_f32_e32 v16, v16
	s_nop 0
	v_mul_f32_e32 v17, 0x45800000, v16
	v_cndmask_b32_e32 v32, v16, v17, vcc
.LBB0_762:
	v_readlane_b32 s88, v239, 18
	v_add_u32_e32 v16, 0xb0, v159
	v_readlane_b32 s90, v239, 20
	v_pk_mul_f32 v[14:15], v[14:15], v[32:33] op_sel_hi:[1,0]
	v_pk_mul_f32 v[12:13], v[12:13], v[32:33] op_sel_hi:[1,0]
	v_mad_i64_i32 v[16:17], s[14:15], v16, s90, 0
	v_lshl_add_u64 v[16:17], v[16:17], 1, v[144:145]
	v_pk_mul_f32 v[18:19], v[10:11], v[32:33] op_sel_hi:[1,0]
	v_pk_mul_f32 v[10:11], v[8:9], v[32:33] op_sel_hi:[1,0]
	v_cvt_pk_bf16_f32 v8, v12, v13
	v_cvt_pk_bf16_f32 v9, v14, v15
	s_and_b64 vcc, exec, s[38:39]
	v_cvt_pk_bf16_f32 v10, v10, v11
	v_cvt_pk_bf16_f32 v11, v18, v19
	global_store_dwordx4 v[16:17], v[8:11], off nt
	s_mov_b64 s[14:15], -1
	v_readlane_b32 s89, v239, 19
	v_pk_mul_f32 v[8:9], v[2:3], v[32:33] op_sel_hi:[1,0]
	v_pk_mul_f32 v[2:3], v[0:1], v[32:33] op_sel_hi:[1,0]
	v_readlane_b32 s91, v239, 21
	v_pk_mul_f32 v[6:7], v[6:7], v[32:33] op_sel_hi:[1,0]
	v_pk_mul_f32 v[4:5], v[4:5], v[32:33] op_sel_hi:[1,0]
	v_cvt_pk_bf16_f32 v1, v6, v7
	v_cvt_pk_bf16_f32 v2, v2, v3
	v_cvt_pk_bf16_f32 v3, v8, v9
	s_nop 0
	v_cvt_pk_bf16_f32 v0, v4, v5
	global_store_dwordx4 v[16:17], v[0:3], off offset:256 nt
	s_cbranch_vccnz .LBB0_735
	s_and_b64 vcc, exec, s[12:13]
	s_cbranch_vccz .LBB0_734
	v_lshl_or_b32 v0, s73, 8, v147
	v_ashrrev_i32_e32 v1, 31, v0
	v_lshlrev_b64 v[0:1], 7, v[0:1]
	v_lshl_add_u64 v[0:1], v[136:137], 0, v[0:1]
	s_and_b64 vcc, exec, s[42:43]
	s_cbranch_vccz .LBB0_768
	v_mov_b32_e32 v2, 0
	s_and_saveexec_b64 s[14:15], s[36:37]
	s_cbranch_execz .LBB0_767
	global_load_dword v2, v[0:1], off

; #define LAS __attribute__((address_space(3)))
; DEVI unsigned pk_bf16(float lo, float hi) { unsigned r; asm("v_cvt_pk_bf16_f32 %0, %1, %2" : "=v"(r) : "v"(lo), "v"(hi)); return r; }
; DEVI float row_rstd(const LAS float* rsl, int r) { return rsqrtf((rsl[r] + rsl[256 + r]) * (1.0f / DM) + 1e-6f); }
;     DEVI void operator()(const f32x4 (&acc)[2][2][4][2], const Unit& u, int wr, int wc, int fr, int fq, const LAS float* rsl) const {
;         bf16_t* const O = O_; const int ldc = ldc_; const float* const rs = rs_; const int rsn = rsn_;
;         const int row0 = u.pm * BM + wr * 64 + fr, col0 = u.pn * BM + wc * 32 + 8 * fq;
; #pragma unroll
;         for (int ai = 0; ai < 2; ++ai)
; #pragma unroll
;             for (int m = 0; m < 4; ++m) { bf16_t* rowp = O + (size_t)(row0 + ai * HALF + m * 16) * ldc + col0;
;                 const float sc = rs ? row_rstd(rsl, wr * 64 + fr + ai * HALF + m * 16) : 1.0f;
; #pragma unroll
;                 for (int bj = 0; bj < 2; ++bj) { const f32x4 v0 = acc[ai][bj][m][0] * sc, v1 = acc[ai][bj][m][1] * sc;
;                     u32x4 w; w.x = pk_bf16(v0[0], v0[1]); w.y = pk_bf16(v0[2], v0[3]); w.z = pk_bf16(v1[0], v1[1]); w.w = pk_bf16(v1[2], v1[3]);
;                     *(u32x4*)(rowp + bj * HALF) = w; } }
;     }
.LBB0_803:
	v_lshl_or_b32 v144, s73, 8, v152
	v_readlane_b32 s14, v239, 22
	v_lshl_add_u32 v159, s74, 8, v149
	v_ashrrev_i32_e32 v145, 31, v144
	v_readlane_b32 s15, v239, 23
	v_pk_mul_f32 v[126:127], v[126:127], v[148:149] op_sel_hi:[1,0]
	v_pk_mul_f32 v[124:125], v[124:125], v[148:149] op_sel_hi:[1,0]
	v_lshl_add_u64 v[144:145], v[144:145], 1, s[14:15]
	v_mad_i64_i32 v[162:163], s[14:15], v159, s82, 0
	v_lshl_add_u64 v[162:163], v[162:163], 1, v[144:145]
	v_pk_mul_f32 v[164:165], v[122:123], v[148:149] op_sel_hi:[1,0]
	v_pk_mul_f32 v[122:123], v[120:121], v[148:149] op_sel_hi:[1,0]
	v_cvt_pk_bf16_f32 v120, v124, v125
	v_cvt_pk_bf16_f32 v121, v126, v127
	v_pk_mul_f32 v[116:117], v[116:117], v[148:149] op_sel_hi:[1,0]
	v_cvt_pk_bf16_f32 v122, v122, v123
	v_cvt_pk_bf16_f32 v123, v164, v165
	global_store_dwordx4 v[162:163], v[120:123], off nt
	v_pk_mul_f32 v[118:119], v[118:119], v[148:149] op_sel_hi:[1,0]
	s_and_b64 vcc, exec, s[40:41]
	v_pk_mul_f32 v[120:121], v[114:115], v[148:149] op_sel_hi:[1,0]
	v_pk_mul_f32 v[114:115], v[112:113], v[148:149] op_sel_hi:[1,0]
	v_cvt_pk_bf16_f32 v112, v116, v117
	v_cvt_pk_bf16_f32 v113, v118, v119
	s_nop 0
	v_cvt_pk_bf16_f32 v114, v114, v115
	v_cvt_pk_bf16_f32 v115, v120, v121
	global_store_dwordx4 v[162:163], v[112:115], off offset:256 nt
	s_nop 1
	v_add_u32_e32 v112, 64, v160
	s_cbranch_vccnz .LBB0_805
	ds_read2st64_b32 v[114:115], v112 offset1:4
	s_waitcnt lgkmcnt(0)
	v_add_f32_e32 v113, v114, v115
	v_fmamk_f32 v113, v113, 0x3a000000, v158
	v_mul_f32_e32 v114, 0x4b800000, v113
	v_cmp_gt_f32_e32 vcc, s51, v113
	s_nop 1
	v_cndmask_b32_e32 v113, v113, v114, vcc
	v_rsq_f32_e32 v113, v113
	s_nop 0
	v_mul_f32_e32 v114, 0x45800000, v113
	v_cndmask_b32_e32 v146, v113, v114, vcc
.LBB0_805:
	v_or_b32_e32 v113, 16, v159
	v_mad_i64_i32 v[114:115], s[14:15], v113, s82, 0
	v_lshl_add_u64 v[114:115], v[114:115], 1, v[144:145]
	v_pk_mul_f32 v[110:111], v[110:111], v[146:147] op_sel_hi:[1,0]
	v_pk_mul_f32 v[108:109], v[108:109], v[146:147] op_sel_hi:[1,0]
	v_pk_mul_f32 v[116:117], v[106:107], v[146:147] op_sel_hi:[1,0]
	v_pk_mul_f32 v[106:107], v[104:105], v[146:147] op_sel_hi:[1,0]
	v_cvt_pk_bf16_f32 v104, v108, v109
	v_cvt_pk_bf16_f32 v105, v110, v111
	v_pk_mul_f32 v[102:103], v[102:103], v[146:147] op_sel_hi:[1,0]
	v_cvt_pk_bf16_f32 v106, v106, v107
	v_cvt_pk_bf16_f32 v107, v116, v117
	global_store_dwordx4 v[114:115], v[104:107], off nt
	v_pk_mul_f32 v[100:101], v[100:101], v[146:147] op_sel_hi:[1,0]
	s_and_b64 vcc, exec, s[40:41]
	v_pk_mul_f32 v[104:105], v[98:99], v[146:147] op_sel_hi:[1,0]
	v_pk_mul_f32 v[98:99], v[96:97], v[146:147] op_sel_hi:[1,0]
	v_cvt_pk_bf16_f32 v96, v100, v101
	v_cvt_pk_bf16_f32 v97, v102, v103
	s_nop 0
	v_cvt_pk_bf16_f32 v98, v98, v99
	v_cvt_pk_bf16_f32 v99, v104, v105
	global_store_dwordx4 v[114:115], v[96:99], off offset:256 nt
	s_nop 1
	v_mov_b32_e32 v96, 1.0
	v_add_u32_e32 v97, 0x80, v160
	v_mov_b32_e32 v98, 1.0
	s_cbranch_vccnz .LBB0_807
	ds_read2st64_b32 v[98:99], v97 offset1:4
	s_waitcnt lgkmcnt(0)
	v_add_f32_e32 v98, v98, v99
	v_fmamk_f32 v98, v98, 0x3a000000, v158
	v_mul_f32_e32 v99, 0x4b800000, v98
	v_cmp_gt_f32_e32 vcc, s51, v98
	s_nop 1
	v_cndmask_b32_e32 v98, v98, v99, vcc
	v_rsq_f32_e32 v98, v98
	s_nop 0
	v_mul_f32_e32 v99, 0x45800000, v98
	v_cndmask_b32_e32 v98, v98, v99, vcc
.LBB0_807:
	v_or_b32_e32 v99, 32, v159
	v_mad_i64_i32 v[100:101], s[14:15], v99, s82, 0
	v_lshl_add_u64 v[100:101], v[100:101], 1, v[144:145]
	v_pk_mul_f32 v[94:95], v[94:95], v[98:99] op_sel_hi:[1,0]
	v_pk_mul_f32 v[92:93], v[92:93], v[98:99] op_sel_hi:[1,0]
	v_pk_mul_f32 v[102:103], v[90:91], v[98:99] op_sel_hi:[1,0]
	v_pk_mul_f32 v[90:91], v[88:89], v[98:99] op_sel_hi:[1,0]
	v_cvt_pk_bf16_f32 v88, v92, v93
	v_cvt_pk_bf16_f32 v89, v94, v95
	v_pk_mul_f32 v[84:85], v[84:85], v[98:99] op_sel_hi:[1,0]
	v_cvt_pk_bf16_f32 v90, v90, v91
	v_cvt_pk_bf16_f32 v91, v102, v103
	global_store_dwordx4 v[100:101], v[88:91], off nt
	v_pk_mul_f32 v[86:87], v[86:87], v[98:99] op_sel_hi:[1,0]
	s_and_b64 vcc, exec, s[40:41]
	v_pk_mul_f32 v[88:89], v[82:83], v[98:99] op_sel_hi:[1,0]
	v_pk_mul_f32 v[82:83], v[80:81], v[98:99] op_sel_hi:[1,0]
	v_cvt_pk_bf16_f32 v80, v84, v85
	v_cvt_pk_bf16_f32 v81, v86, v87
	s_nop 0
	v_cvt_pk_bf16_f32 v82, v82, v83
	v_cvt_pk_bf16_f32 v83, v88, v89
	global_store_dwordx4 v[100:101], v[80:83], off offset:256 nt
	s_nop 1
	v_add_u32_e32 v80, 0xc0, v160
	s_cbranch_vccnz .LBB0_809
	ds_read2st64_b32 v[82:83], v80 offset1:4
	s_waitcnt lgkmcnt(0)
	v_add_f32_e32 v81, v82, v83
	v_fmamk_f32 v81, v81, 0x3a000000, v158
	v_mul_f32_e32 v82, 0x4b800000, v81
	v_cmp_gt_f32_e32 vcc, s51, v81
	s_nop 1
	v_cndmask_b32_e32 v81, v81, v82, vcc
	v_rsq_f32_e32 v81, v81
	s_nop 0
	v_mul_f32_e32 v82, 0x45800000, v81
	v_cndmask_b32_e32 v96, v81, v82, vcc
.LBB0_809:
	v_or_b32_e32 v81, 48, v159
	v_mad_i64_i32 v[82:83], s[14:15], v81, s82, 0
	v_lshl_add_u64 v[82:83], v[82:83], 1, v[144:145]
	v_pk_mul_f32 v[78:79], v[78:79], v[96:97] op_sel_hi:[1,0]
	v_pk_mul_f32 v[76:77], v[76:77], v[96:97] op_sel_hi:[1,0]
	v_pk_mul_f32 v[84:85], v[74:75], v[96:97] op_sel_hi:[1,0]
	v_pk_mul_f32 v[74:75], v[72:73], v[96:97] op_sel_hi:[1,0]
	v_cvt_pk_bf16_f32 v72, v76, v77
	v_cvt_pk_bf16_f32 v73, v78, v79
	v_pk_mul_f32 v[68:69], v[68:69], v[96:97] op_sel_hi:[1,0]
	v_cvt_pk_bf16_f32 v74, v74, v75
	v_cvt_pk_bf16_f32 v75, v84, v85
	global_store_dwordx4 v[82:83], v[72:75], off nt
	v_pk_mul_f32 v[70:71], v[70:71], v[96:97] op_sel_hi:[1,0]
	s_and_b64 vcc, exec, s[40:41]
	v_pk_mul_f32 v[72:73], v[66:67], v[96:97] op_sel_hi:[1,0]
	v_pk_mul_f32 v[66:67], v[64:65], v[96:97] op_sel_hi:[1,0]
	v_cvt_pk_bf16_f32 v64, v68, v69
	v_cvt_pk_bf16_f32 v65, v70, v71
	s_nop 0
	v_cvt_pk_bf16_f32 v66, v66, v67
	v_cvt_pk_bf16_f32 v67, v72, v73
	global_store_dwordx4 v[82:83], v[64:67], off offset:256 nt
	s_nop 1
	v_mov_b32_e32 v64, 1.0
	v_mov_b32_e32 v66, 1.0
	s_cbranch_vccnz .LBB0_811
	ds_read2st64_b32 v[66:67], v160 offset0:2 offset1:6
	s_waitcnt lgkmcnt(0)
	v_add_f32_e32 v65, v66, v67
	v_fmamk_f32 v65, v65, 0x3a000000, v158
	v_mul_f32_e32 v66, 0x4b800000, v65
	v_cmp_gt_f32_e32 vcc, s51, v65
	s_nop 1
	v_cndmask_b32_e32 v65, v65, v66, vcc
	v_rsq_f32_e32 v65, v65
	s_nop 0
	v_mul_f32_e32 v66, 0x45800000, v65
	v_cndmask_b32_e32 v66, v65, v66, vcc
; #define LAS __attribute__((address_space(3)))
; DEVI unsigned pk_bf16(float lo, float hi) { unsigned r; asm("v_cvt_pk_bf16_f32 %0, %1, %2" : "=v"(r) : "v"(lo), "v"(hi)); return r; }
; DEVI float row_rstd(const LAS float* rsl, int r) { return rsqrtf((rsl[r] + rsl[256 + r]) * (1.0f / DM) + 1e-6f); }
;     DEVI void operator()(const f32x4 (&acc)[2][2][4][2], const Unit& u, int wr, int wc, int fr, int fq, const LAS float* rsl) const {
;         bf16_t* const O = O_; const int ldc = ldc_; const float* const rs = rs_; const int rsn = rsn_;
;         const int row0 = u.pm * BM + wr * 64 + fr, col0 = u.pn * BM + wc * 32 + 8 * fq;
; #pragma unroll
;         for (int ai = 0; ai < 2; ++ai)
; #pragma unroll
;             for (int m = 0; m < 4; ++m) { bf16_t* rowp = O + (size_t)(row0 + ai * HALF + m * 16) * ldc + col0;
;                 const float sc = rs ? row_rstd(rsl, wr * 64 + fr + ai * HALF + m * 16) : 1.0f;
; #pragma unroll
;                 for (int bj = 0; bj < 2; ++bj) { const f32x4 v0 = acc[ai][bj][m][0] * sc, v1 = acc[ai][bj][m][1] * sc;
;                     u32x4 w; w.x = pk_bf16(v0[0], v0[1]); w.y = pk_bf16(v0[2], v0[3]); w.z = pk_bf16(v1[0], v1[1]); w.w = pk_bf16(v1[2], v1[3]);
;                     *(u32x4*)(rowp + bj * HALF) = w; } }
;     }
; template <class Epi>
; DEVI void gemm_phase(LAS unsigned char* lds, const bf16_t* gA, const bf16_t* gBt, const int lda, const int ldb, const int K, const StaticOrder S_, const Epi E) {
;     ...
;         if (!has_next) break;
; #pragma unroll
;         for (int a = 0; a < 2; ++a)
; #pragma unroll
;             for (int b = 0; b < 2; ++b)
; #pragma unroll
;                 for (int m = 0; m < 4; ++m)
; #pragma unroll
;                     for (int n = 0; n < 2; ++n) acc[a][b][m][n] = (f32x4){0.f, 0.f, 0.f, 0.f};
;         cur = nxt; cA = nA; cB = nB; ++ui;
;         rs_prefetch(cur, ui & 1);
.LBB0_811:
	v_add_u32_e32 v65, 0x80, v159
	v_mad_i64_i32 v[68:69], s[14:15], v65, s82, 0
	v_lshl_add_u64 v[68:69], v[68:69], 1, v[144:145]
	v_pk_mul_f32 v[62:63], v[62:63], v[66:67] op_sel_hi:[1,0]
	v_pk_mul_f32 v[60:61], v[60:61], v[66:67] op_sel_hi:[1,0]
	v_pk_mul_f32 v[70:71], v[58:59], v[66:67] op_sel_hi:[1,0]
	v_pk_mul_f32 v[58:59], v[56:57], v[66:67] op_sel_hi:[1,0]
	v_cvt_pk_bf16_f32 v56, v60, v61
	v_cvt_pk_bf16_f32 v57, v62, v63
	s_and_b64 vcc, exec, s[40:41]
	v_cvt_pk_bf16_f32 v58, v58, v59
	v_cvt_pk_bf16_f32 v59, v70, v71
	global_store_dwordx4 v[68:69], v[56:59], off nt
	v_pk_mul_f32 v[54:55], v[54:55], v[66:67] op_sel_hi:[1,0]
	v_pk_mul_f32 v[52:53], v[52:53], v[66:67] op_sel_hi:[1,0]
	v_pk_mul_f32 v[56:57], v[50:51], v[66:67] op_sel_hi:[1,0]
	v_pk_mul_f32 v[50:51], v[48:49], v[66:67] op_sel_hi:[1,0]
	v_cvt_pk_bf16_f32 v48, v52, v53
	v_cvt_pk_bf16_f32 v49, v54, v55
	s_nop 0
	v_cvt_pk_bf16_f32 v50, v50, v51
	v_cvt_pk_bf16_f32 v51, v56, v57
	global_store_dwordx4 v[68:69], v[48:51], off offset:256 nt
	s_cbranch_vccnz .LBB0_813
	ds_read2st64_b32 v[48:49], v112 offset0:2 offset1:6
	s_waitcnt lgkmcnt(0)
	v_add_f32_e32 v48, v48, v49
	v_fmamk_f32 v48, v48, 0x3a000000, v158
	v_mul_f32_e32 v49, 0x4b800000, v48
	v_cmp_gt_f32_e32 vcc, s51, v48
	s_nop 1
	v_cndmask_b32_e32 v48, v48, v49, vcc
	v_rsq_f32_e32 v48, v48
	s_nop 0
	v_mul_f32_e32 v49, 0x45800000, v48
	v_cndmask_b32_e32 v64, v48, v49, vcc
.LBB0_813:
	s_nop 0
	v_add_u32_e32 v48, 0x90, v159
	v_mad_i64_i32 v[48:49], s[14:15], v48, s82, 0
	v_lshl_add_u64 v[48:49], v[48:49], 1, v[144:145]
	v_pk_mul_f32 v[46:47], v[46:47], v[64:65] op_sel_hi:[1,0]
	v_pk_mul_f32 v[44:45], v[44:45], v[64:65] op_sel_hi:[1,0]
	v_pk_mul_f32 v[50:51], v[42:43], v[64:65] op_sel_hi:[1,0]
	v_pk_mul_f32 v[42:43], v[40:41], v[64:65] op_sel_hi:[1,0]
	v_cvt_pk_bf16_f32 v40, v44, v45
	v_cvt_pk_bf16_f32 v41, v46, v47
	v_pk_mul_f32 v[36:37], v[36:37], v[64:65] op_sel_hi:[1,0]
	v_cvt_pk_bf16_f32 v42, v42, v43
	v_cvt_pk_bf16_f32 v43, v50, v51
	global_store_dwordx4 v[48:49], v[40:43], off nt
	v_pk_mul_f32 v[38:39], v[38:39], v[64:65] op_sel_hi:[1,0]
	s_and_b64 vcc, exec, s[40:41]
	v_pk_mul_f32 v[40:41], v[34:35], v[64:65] op_sel_hi:[1,0]
	v_pk_mul_f32 v[34:35], v[32:33], v[64:65] op_sel_hi:[1,0]
	v_cvt_pk_bf16_f32 v32, v36, v37
	v_cvt_pk_bf16_f32 v33, v38, v39
	s_nop 0
	v_cvt_pk_bf16_f32 v34, v34, v35
	v_cvt_pk_bf16_f32 v35, v40, v41
	global_store_dwordx4 v[48:49], v[32:35], off offset:256 nt
	s_nop 1
	v_mov_b32_e32 v32, 1.0
	v_mov_b32_e32 v34, 1.0
	s_cbranch_vccnz .LBB0_815
	ds_read2st64_b32 v[34:35], v97 offset0:2 offset1:6
	s_waitcnt lgkmcnt(0)
	v_add_f32_e32 v33, v34, v35
	v_fmamk_f32 v33, v33, 0x3a000000, v158
	v_mul_f32_e32 v34, 0x4b800000, v33
	v_cmp_gt_f32_e32 vcc, s51, v33
	s_nop 1
	v_cndmask_b32_e32 v33, v33, v34, vcc
	v_rsq_f32_e32 v33, v33
	s_nop 0
	v_mul_f32_e32 v34, 0x45800000, v33
	v_cndmask_b32_e32 v34, v33, v34, vcc
.LBB0_815:
	v_add_u32_e32 v33, 0xa0, v159
	v_mad_i64_i32 v[36:37], s[14:15], v33, s82, 0
	v_lshl_add_u64 v[36:37], v[36:37], 1, v[144:145]
	v_pk_mul_f32 v[30:31], v[30:31], v[34:35] op_sel_hi:[1,0]
	v_pk_mul_f32 v[28:29], v[28:29], v[34:35] op_sel_hi:[1,0]
	v_pk_mul_f32 v[38:39], v[26:27], v[34:35] op_sel_hi:[1,0]
	v_pk_mul_f32 v[26:27], v[24:25], v[34:35] op_sel_hi:[1,0]
	v_cvt_pk_bf16_f32 v24, v28, v29
	v_cvt_pk_bf16_f32 v25, v30, v31
	s_and_b64 vcc, exec, s[40:41]
	v_cvt_pk_bf16_f32 v26, v26, v27
	v_cvt_pk_bf16_f32 v27, v38, v39
	global_store_dwordx4 v[36:37], v[24:27], off nt
	v_pk_mul_f32 v[22:23], v[22:23], v[34:35] op_sel_hi:[1,0]
	v_pk_mul_f32 v[20:21], v[20:21], v[34:35] op_sel_hi:[1,0]
	v_pk_mul_f32 v[24:25], v[18:19], v[34:35] op_sel_hi:[1,0]
	v_pk_mul_f32 v[18:19], v[16:17], v[34:35] op_sel_hi:[1,0]
	v_cvt_pk_bf16_f32 v16, v20, v21
	v_cvt_pk_bf16_f32 v17, v22, v23
	s_nop 0
	v_cvt_pk_bf16_f32 v18, v18, v19
	v_cvt_pk_bf16_f32 v19, v24, v25
	global_store_dwordx4 v[36:37], v[16:19], off offset:256 nt
	s_cbranch_vccnz .LBB0_817
	ds_read2st64_b32 v[16:17], v80 offset0:2 offset1:6
	s_waitcnt lgkmcnt(0)
	v_add_f32_e32 v16, v16, v17
	v_fmamk_f32 v16, v16, 0x3a000000, v158
	v_mul_f32_e32 v17, 0x4b800000, v16
	v_cmp_gt_f32_e32 vcc, s51, v16
	s_nop 1
	v_cndmask_b32_e32 v16, v16, v17, vcc
	v_rsq_f32_e32 v16, v16
	s_nop 0
	v_mul_f32_e32 v17, 0x45800000, v16
	v_cndmask_b32_e32 v32, v16, v17, vcc
.LBB0_817:
	s_nop 0
	v_add_u32_e32 v16, 0xb0, v159
	v_mad_i64_i32 v[16:17], s[14:15], v16, s82, 0
	v_lshl_add_u64 v[16:17], v[16:17], 1, v[144:145]
	v_pk_mul_f32 v[14:15], v[14:15], v[32:33] op_sel_hi:[1,0]
	v_pk_mul_f32 v[12:13], v[12:13], v[32:33] op_sel_hi:[1,0]
	v_pk_mul_f32 v[18:19], v[10:11], v[32:33] op_sel_hi:[1,0]
	v_pk_mul_f32 v[10:11], v[8:9], v[32:33] op_sel_hi:[1,0]
	v_cvt_pk_bf16_f32 v8, v12, v13
	v_cvt_pk_bf16_f32 v9, v14, v15
	s_and_b64 vcc, exec, s[38:39]
	v_cvt_pk_bf16_f32 v10, v10, v11
	v_cvt_pk_bf16_f32 v11, v18, v19
	global_store_dwordx4 v[16:17], v[8:11], off nt
	s_mov_b64 s[14:15], -1
	v_pk_mul_f32 v[6:7], v[6:7], v[32:33] op_sel_hi:[1,0]
	v_pk_mul_f32 v[8:9], v[2:3], v[32:33] op_sel_hi:[1,0]
	v_pk_mul_f32 v[2:3], v[0:1], v[32:33] op_sel_hi:[1,0]
	v_pk_mul_f32 v[4:5], v[4:5], v[32:33] op_sel_hi:[1,0]
	v_cvt_pk_bf16_f32 v1, v6, v7
	v_cvt_pk_bf16_f32 v2, v2, v3
	v_cvt_pk_bf16_f32 v3, v8, v9
	s_nop 0
	v_cvt_pk_bf16_f32 v0, v4, v5
	global_store_dwordx4 v[16:17], v[0:3], off offset:256 nt
	s_cbranch_vccnz .LBB0_791
	s_and_b64 vcc, exec, s[12:13]
	s_cbranch_vccz .LBB0_790
	v_lshl_or_b32 v0, s72, 8, v147
	v_ashrrev_i32_e32 v1, 31, v0
	v_lshlrev_b64 v[0:1], 7, v[0:1]
	v_lshl_add_u64 v[0:1], v[136:137], 0, v[0:1]
	s_and_b64 vcc, exec, s[42:43]
	s_cbranch_vccz .LBB0_823
	v_mov_b32_e32 v2, 0
	s_and_saveexec_b64 s[14:15], s[36:37]
	s_cbranch_execz .LBB0_822
	global_load_dword v2, v[0:1], off

; #define LAS __attribute__((address_space(3)))
; DEVI unsigned pk_bf16(float lo, float hi) { unsigned r; asm("v_cvt_pk_bf16_f32 %0, %1, %2" : "=v"(r) : "v"(lo), "v"(hi)); return r; }
; DEVI float row_rstd(const LAS float* rsl, int r) { return rsqrtf((rsl[r] + rsl[256 + r]) * (1.0f / DM) + 1e-6f); }
;     DEVI void operator()(const f32x4 (&acc)[2][2][4][2], const Unit& u, int wr, int wc, int fr, int fq, const LAS float* rsl) const {
;         bf16_t* const O = O_; const int ldc = ldc_; const float* const rs = rs_; const int rsn = rsn_;
;         const int row0 = u.pm * BM + wr * 64 + fr, col0 = u.pn * BM + wc * 32 + 8 * fq;
; #pragma unroll
;         for (int ai = 0; ai < 2; ++ai)
; #pragma unroll
;             for (int m = 0; m < 4; ++m) { bf16_t* rowp = O + (size_t)(row0 + ai * HALF + m * 16) * ldc + col0;
;                 const float sc = rs ? row_rstd(rsl, wr * 64 + fr + ai * HALF + m * 16) : 1.0f;
; #pragma unroll
;                 for (int bj = 0; bj < 2; ++bj) { const f32x4 v0 = acc[ai][bj][m][0] * sc, v1 = acc[ai][bj][m][1] * sc;
;                     u32x4 w; w.x = pk_bf16(v0[0], v0[1]); w.y = pk_bf16(v0[2], v0[3]); w.z = pk_bf16(v1[0], v1[1]); w.w = pk_bf16(v1[2], v1[3]);
;                     *(u32x4*)(rowp + bj * HALF) = w; } }
;     }
.LBB0_858:
	v_lshl_or_b32 v144, s73, 8, v152
	v_readlane_b32 s14, v239, 32
	v_lshl_add_u32 v159, s74, 8, v149
	v_ashrrev_i32_e32 v145, 31, v144
	v_readlane_b32 s15, v239, 33
	v_pk_mul_f32 v[126:127], v[126:127], v[148:149] op_sel_hi:[1,0]
	v_pk_mul_f32 v[124:125], v[124:125], v[148:149] op_sel_hi:[1,0]
	v_lshl_add_u64 v[144:145], v[144:145], 1, s[14:15]
	v_mad_i64_i32 v[162:163], s[14:15], v159, s86, 0
	v_lshl_add_u64 v[162:163], v[162:163], 1, v[144:145]
	v_pk_mul_f32 v[164:165], v[122:123], v[148:149] op_sel_hi:[1,0]
	v_pk_mul_f32 v[122:123], v[120:121], v[148:149] op_sel_hi:[1,0]
	v_cvt_pk_bf16_f32 v120, v124, v125
	v_cvt_pk_bf16_f32 v121, v126, v127
	v_pk_mul_f32 v[116:117], v[116:117], v[148:149] op_sel_hi:[1,0]
	v_cvt_pk_bf16_f32 v122, v122, v123
	v_cvt_pk_bf16_f32 v123, v164, v165
	global_store_dwordx4 v[162:163], v[120:123], off nt
	v_pk_mul_f32 v[118:119], v[118:119], v[148:149] op_sel_hi:[1,0]
	s_and_b64 vcc, exec, s[40:41]
	v_pk_mul_f32 v[120:121], v[114:115], v[148:149] op_sel_hi:[1,0]
	v_pk_mul_f32 v[114:115], v[112:113], v[148:149] op_sel_hi:[1,0]
	v_cvt_pk_bf16_f32 v112, v116, v117
	v_cvt_pk_bf16_f32 v113, v118, v119
	s_nop 0
	v_cvt_pk_bf16_f32 v114, v114, v115
	v_cvt_pk_bf16_f32 v115, v120, v121
	global_store_dwordx4 v[162:163], v[112:115], off offset:256 nt
	s_nop 1
	v_add_u32_e32 v112, 64, v160
	s_cbranch_vccnz .LBB0_860
	ds_read2st64_b32 v[114:115], v112 offset1:4
	s_waitcnt lgkmcnt(0)
	v_add_f32_e32 v113, v114, v115
	v_fmamk_f32 v113, v113, 0x3a000000, v158
	v_mul_f32_e32 v114, 0x4b800000, v113
	v_cmp_gt_f32_e32 vcc, s51, v113
	s_nop 1
	v_cndmask_b32_e32 v113, v113, v114, vcc
	v_rsq_f32_e32 v113, v113
	s_nop 0
	v_mul_f32_e32 v114, 0x45800000, v113
	v_cndmask_b32_e32 v146, v113, v114, vcc
.LBB0_860:
	v_or_b32_e32 v113, 16, v159
	v_mad_i64_i32 v[114:115], s[14:15], v113, s86, 0
	v_lshl_add_u64 v[114:115], v[114:115], 1, v[144:145]
	v_pk_mul_f32 v[110:111], v[110:111], v[146:147] op_sel_hi:[1,0]
	v_pk_mul_f32 v[108:109], v[108:109], v[146:147] op_sel_hi:[1,0]
	v_pk_mul_f32 v[116:117], v[106:107], v[146:147] op_sel_hi:[1,0]
	v_pk_mul_f32 v[106:107], v[104:105], v[146:147] op_sel_hi:[1,0]
	v_cvt_pk_bf16_f32 v104, v108, v109
	v_cvt_pk_bf16_f32 v105, v110, v111
	v_pk_mul_f32 v[102:103], v[102:103], v[146:147] op_sel_hi:[1,0]
	v_cvt_pk_bf16_f32 v106, v106, v107
	v_cvt_pk_bf16_f32 v107, v116, v117
	global_store_dwordx4 v[114:115], v[104:107], off nt
	v_pk_mul_f32 v[100:101], v[100:101], v[146:147] op_sel_hi:[1,0]
	s_and_b64 vcc, exec, s[40:41]
	v_pk_mul_f32 v[104:105], v[98:99], v[146:147] op_sel_hi:[1,0]
	v_pk_mul_f32 v[98:99], v[96:97], v[146:147] op_sel_hi:[1,0]
	v_cvt_pk_bf16_f32 v96, v100, v101
	v_cvt_pk_bf16_f32 v97, v102, v103
	s_nop 0
	v_cvt_pk_bf16_f32 v98, v98, v99
	v_cvt_pk_bf16_f32 v99, v104, v105
	global_store_dwordx4 v[114:115], v[96:99], off offset:256 nt
	s_nop 1
	v_mov_b32_e32 v96, 1.0
	v_add_u32_e32 v97, 0x80, v160
	v_mov_b32_e32 v98, 1.0
	s_cbranch_vccnz .LBB0_862
	ds_read2st64_b32 v[98:99], v97 offset1:4
	s_waitcnt lgkmcnt(0)
	v_add_f32_e32 v98, v98, v99
	v_fmamk_f32 v98, v98, 0x3a000000, v158
	v_mul_f32_e32 v99, 0x4b800000, v98
	v_cmp_gt_f32_e32 vcc, s51, v98
	s_nop 1
	v_cndmask_b32_e32 v98, v98, v99, vcc
	v_rsq_f32_e32 v98, v98
	s_nop 0
	v_mul_f32_e32 v99, 0x45800000, v98
	v_cndmask_b32_e32 v98, v98, v99, vcc
.LBB0_862:
	v_or_b32_e32 v99, 32, v159
	v_mad_i64_i32 v[100:101], s[14:15], v99, s86, 0
	v_lshl_add_u64 v[100:101], v[100:101], 1, v[144:145]
	v_pk_mul_f32 v[94:95], v[94:95], v[98:99] op_sel_hi:[1,0]
	v_pk_mul_f32 v[92:93], v[92:93], v[98:99] op_sel_hi:[1,0]
	v_pk_mul_f32 v[102:103], v[90:91], v[98:99] op_sel_hi:[1,0]
	v_pk_mul_f32 v[90:91], v[88:89], v[98:99] op_sel_hi:[1,0]
	v_cvt_pk_bf16_f32 v88, v92, v93
	v_cvt_pk_bf16_f32 v89, v94, v95
	v_pk_mul_f32 v[84:85], v[84:85], v[98:99] op_sel_hi:[1,0]
	v_cvt_pk_bf16_f32 v90, v90, v91
	v_cvt_pk_bf16_f32 v91, v102, v103
	global_store_dwordx4 v[100:101], v[88:91], off nt
	v_pk_mul_f32 v[86:87], v[86:87], v[98:99] op_sel_hi:[1,0]
	s_and_b64 vcc, exec, s[40:41]
	v_pk_mul_f32 v[88:89], v[82:83], v[98:99] op_sel_hi:[1,0]
	v_pk_mul_f32 v[82:83], v[80:81], v[98:99] op_sel_hi:[1,0]
	v_cvt_pk_bf16_f32 v80, v84, v85
	v_cvt_pk_bf16_f32 v81, v86, v87
	s_nop 0
	v_cvt_pk_bf16_f32 v82, v82, v83
	v_cvt_pk_bf16_f32 v83, v88, v89
	global_store_dwordx4 v[100:101], v[80:83], off offset:256 nt
	s_nop 1
	v_add_u32_e32 v80, 0xc0, v160
	s_cbranch_vccnz .LBB0_864
	ds_read2st64_b32 v[82:83], v80 offset1:4
	s_waitcnt lgkmcnt(0)
	v_add_f32_e32 v81, v82, v83
	v_fmamk_f32 v81, v81, 0x3a000000, v158
	v_mul_f32_e32 v82, 0x4b800000, v81
	v_cmp_gt_f32_e32 vcc, s51, v81
	s_nop 1
	v_cndmask_b32_e32 v81, v81, v82, vcc
	v_rsq_f32_e32 v81, v81
	s_nop 0
	v_mul_f32_e32 v82, 0x45800000, v81
	v_cndmask_b32_e32 v96, v81, v82, vcc
.LBB0_864:
	v_or_b32_e32 v81, 48, v159
	v_mad_i64_i32 v[82:83], s[14:15], v81, s86, 0
	v_lshl_add_u64 v[82:83], v[82:83], 1, v[144:145]
	v_pk_mul_f32 v[78:79], v[78:79], v[96:97] op_sel_hi:[1,0]
	v_pk_mul_f32 v[76:77], v[76:77], v[96:97] op_sel_hi:[1,0]
	v_pk_mul_f32 v[84:85], v[74:75], v[96:97] op_sel_hi:[1,0]
	v_pk_mul_f32 v[74:75], v[72:73], v[96:97] op_sel_hi:[1,0]
	v_cvt_pk_bf16_f32 v72, v76, v77
	v_cvt_pk_bf16_f32 v73, v78, v79
	v_pk_mul_f32 v[68:69], v[68:69], v[96:97] op_sel_hi:[1,0]
	v_cvt_pk_bf16_f32 v74, v74, v75
	v_cvt_pk_bf16_f32 v75, v84, v85
	global_store_dwordx4 v[82:83], v[72:75], off nt
	v_pk_mul_f32 v[70:71], v[70:71], v[96:97] op_sel_hi:[1,0]
	s_and_b64 vcc, exec, s[40:41]
	v_pk_mul_f32 v[72:73], v[66:67], v[96:97] op_sel_hi:[1,0]
	v_pk_mul_f32 v[66:67], v[64:65], v[96:97] op_sel_hi:[1,0]
	v_cvt_pk_bf16_f32 v64, v68, v69
	v_cvt_pk_bf16_f32 v65, v70, v71
	s_nop 0
	v_cvt_pk_bf16_f32 v66, v66, v67
	v_cvt_pk_bf16_f32 v67, v72, v73
	global_store_dwordx4 v[82:83], v[64:67], off offset:256 nt
	s_nop 1
	v_mov_b32_e32 v64, 1.0
	v_mov_b32_e32 v66, 1.0
	s_cbranch_vccnz .LBB0_866
	ds_read2st64_b32 v[66:67], v160 offset0:2 offset1:6
	s_waitcnt lgkmcnt(0)
	v_add_f32_e32 v65, v66, v67
	v_fmamk_f32 v65, v65, 0x3a000000, v158
	v_mul_f32_e32 v66, 0x4b800000, v65
	v_cmp_gt_f32_e32 vcc, s51, v65
	s_nop 1
	v_cndmask_b32_e32 v65, v65, v66, vcc
	v_rsq_f32_e32 v65, v65
	s_nop 0
	v_mul_f32_e32 v66, 0x45800000, v65
	v_cndmask_b32_e32 v66, v65, v66, vcc
; #define LAS __attribute__((address_space(3)))
; DEVI unsigned pk_bf16(float lo, float hi) { unsigned r; asm("v_cvt_pk_bf16_f32 %0, %1, %2" : "=v"(r) : "v"(lo), "v"(hi)); return r; }
; DEVI float row_rstd(const LAS float* rsl, int r) { return rsqrtf((rsl[r] + rsl[256 + r]) * (1.0f / DM) + 1e-6f); }
;     DEVI void operator()(const f32x4 (&acc)[2][2][4][2], const Unit& u, int wr, int wc, int fr, int fq, const LAS float* rsl) const {
;         bf16_t* const O = O_; const int ldc = ldc_; const float* const rs = rs_; const int rsn = rsn_;
;         const int row0 = u.pm * BM + wr * 64 + fr, col0 = u.pn * BM + wc * 32 + 8 * fq;
; #pragma unroll
;         for (int ai = 0; ai < 2; ++ai)
; #pragma unroll
;             for (int m = 0; m < 4; ++m) { bf16_t* rowp = O + (size_t)(row0 + ai * HALF + m * 16) * ldc + col0;
;                 const float sc = rs ? row_rstd(rsl, wr * 64 + fr + ai * HALF + m * 16) : 1.0f;
; #pragma unroll
;                 for (int bj = 0; bj < 2; ++bj) { const f32x4 v0 = acc[ai][bj][m][0] * sc, v1 = acc[ai][bj][m][1] * sc;
;                     u32x4 w; w.x = pk_bf16(v0[0], v0[1]); w.y = pk_bf16(v0[2], v0[3]); w.z = pk_bf16(v1[0], v1[1]); w.w = pk_bf16(v1[2], v1[3]);
;                     *(u32x4*)(rowp + bj * HALF) = w; } }
;     }
; template <class Epi>
; DEVI void gemm_phase(LAS unsigned char* lds, const bf16_t* gA, const bf16_t* gBt, const int lda, const int ldb, const int K, const StaticOrder S_, const Epi E) {
;     ...
;         if (!has_next) break;
; #pragma unroll
;         for (int a = 0; a < 2; ++a)
; #pragma unroll
;             for (int b = 0; b < 2; ++b)
; #pragma unroll
;                 for (int m = 0; m < 4; ++m)
; #pragma unroll
;                     for (int n = 0; n < 2; ++n) acc[a][b][m][n] = (f32x4){0.f, 0.f, 0.f, 0.f};
;         cur = nxt; cA = nA; cB = nB; ++ui;
;         rs_prefetch(cur, ui & 1);
.LBB0_866:
	v_add_u32_e32 v65, 0x80, v159
	v_mad_i64_i32 v[68:69], s[14:15], v65, s86, 0
	v_lshl_add_u64 v[68:69], v[68:69], 1, v[144:145]
	v_pk_mul_f32 v[62:63], v[62:63], v[66:67] op_sel_hi:[1,0]
	v_pk_mul_f32 v[60:61], v[60:61], v[66:67] op_sel_hi:[1,0]
	v_pk_mul_f32 v[70:71], v[58:59], v[66:67] op_sel_hi:[1,0]
	v_pk_mul_f32 v[58:59], v[56:57], v[66:67] op_sel_hi:[1,0]
	v_cvt_pk_bf16_f32 v56, v60, v61
	v_cvt_pk_bf16_f32 v57, v62, v63
	s_and_b64 vcc, exec, s[40:41]
	v_cvt_pk_bf16_f32 v58, v58, v59
	v_cvt_pk_bf16_f32 v59, v70, v71
	global_store_dwordx4 v[68:69], v[56:59], off nt
	v_pk_mul_f32 v[54:55], v[54:55], v[66:67] op_sel_hi:[1,0]
	v_pk_mul_f32 v[52:53], v[52:53], v[66:67] op_sel_hi:[1,0]
	v_pk_mul_f32 v[56:57], v[50:51], v[66:67] op_sel_hi:[1,0]
	v_pk_mul_f32 v[50:51], v[48:49], v[66:67] op_sel_hi:[1,0]
	v_cvt_pk_bf16_f32 v48, v52, v53
	v_cvt_pk_bf16_f32 v49, v54, v55
	s_nop 0
	v_cvt_pk_bf16_f32 v50, v50, v51
	v_cvt_pk_bf16_f32 v51, v56, v57
	global_store_dwordx4 v[68:69], v[48:51], off offset:256 nt
	s_cbranch_vccnz .LBB0_868
	ds_read2st64_b32 v[48:49], v112 offset0:2 offset1:6
	s_waitcnt lgkmcnt(0)
	v_add_f32_e32 v48, v48, v49
	v_fmamk_f32 v48, v48, 0x3a000000, v158
	v_mul_f32_e32 v49, 0x4b800000, v48
	v_cmp_gt_f32_e32 vcc, s51, v48
	s_nop 1
	v_cndmask_b32_e32 v48, v48, v49, vcc
	v_rsq_f32_e32 v48, v48
	s_nop 0
	v_mul_f32_e32 v49, 0x45800000, v48
	v_cndmask_b32_e32 v64, v48, v49, vcc
.LBB0_868:
	s_nop 0
	v_add_u32_e32 v48, 0x90, v159
	v_mad_i64_i32 v[48:49], s[14:15], v48, s86, 0
	v_lshl_add_u64 v[48:49], v[48:49], 1, v[144:145]
	v_pk_mul_f32 v[46:47], v[46:47], v[64:65] op_sel_hi:[1,0]
	v_pk_mul_f32 v[44:45], v[44:45], v[64:65] op_sel_hi:[1,0]
	v_pk_mul_f32 v[50:51], v[42:43], v[64:65] op_sel_hi:[1,0]
	v_pk_mul_f32 v[42:43], v[40:41], v[64:65] op_sel_hi:[1,0]
	v_cvt_pk_bf16_f32 v40, v44, v45
	v_cvt_pk_bf16_f32 v41, v46, v47
	v_pk_mul_f32 v[36:37], v[36:37], v[64:65] op_sel_hi:[1,0]
	v_cvt_pk_bf16_f32 v42, v42, v43
	v_cvt_pk_bf16_f32 v43, v50, v51
	global_store_dwordx4 v[48:49], v[40:43], off nt
	v_pk_mul_f32 v[38:39], v[38:39], v[64:65] op_sel_hi:[1,0]
	s_and_b64 vcc, exec, s[40:41]
	v_pk_mul_f32 v[40:41], v[34:35], v[64:65] op_sel_hi:[1,0]
	v_pk_mul_f32 v[34:35], v[32:33], v[64:65] op_sel_hi:[1,0]
	v_cvt_pk_bf16_f32 v32, v36, v37
	v_cvt_pk_bf16_f32 v33, v38, v39
	s_nop 0
	v_cvt_pk_bf16_f32 v34, v34, v35
	v_cvt_pk_bf16_f32 v35, v40, v41
	global_store_dwordx4 v[48:49], v[32:35], off offset:256 nt
	s_nop 1
	v_mov_b32_e32 v32, 1.0
	v_mov_b32_e32 v34, 1.0
	s_cbranch_vccnz .LBB0_870
	ds_read2st64_b32 v[34:35], v97 offset0:2 offset1:6
	s_waitcnt lgkmcnt(0)
	v_add_f32_e32 v33, v34, v35
	v_fmamk_f32 v33, v33, 0x3a000000, v158
	v_mul_f32_e32 v34, 0x4b800000, v33
	v_cmp_gt_f32_e32 vcc, s51, v33
	s_nop 1
	v_cndmask_b32_e32 v33, v33, v34, vcc
	v_rsq_f32_e32 v33, v33
	s_nop 0
	v_mul_f32_e32 v34, 0x45800000, v33
	v_cndmask_b32_e32 v34, v33, v34, vcc
.LBB0_870:
	v_add_u32_e32 v33, 0xa0, v159
	v_mad_i64_i32 v[36:37], s[14:15], v33, s86, 0
	v_lshl_add_u64 v[36:37], v[36:37], 1, v[144:145]
	v_pk_mul_f32 v[30:31], v[30:31], v[34:35] op_sel_hi:[1,0]
	v_pk_mul_f32 v[28:29], v[28:29], v[34:35] op_sel_hi:[1,0]
	v_pk_mul_f32 v[38:39], v[26:27], v[34:35] op_sel_hi:[1,0]
	v_pk_mul_f32 v[26:27], v[24:25], v[34:35] op_sel_hi:[1,0]
	v_cvt_pk_bf16_f32 v24, v28, v29
	v_cvt_pk_bf16_f32 v25, v30, v31
	s_and_b64 vcc, exec, s[40:41]
	v_cvt_pk_bf16_f32 v26, v26, v27
	v_cvt_pk_bf16_f32 v27, v38, v39
	global_store_dwordx4 v[36:37], v[24:27], off nt
	v_pk_mul_f32 v[22:23], v[22:23], v[34:35] op_sel_hi:[1,0]
	v_pk_mul_f32 v[20:21], v[20:21], v[34:35] op_sel_hi:[1,0]
	v_pk_mul_f32 v[24:25], v[18:19], v[34:35] op_sel_hi:[1,0]
	v_pk_mul_f32 v[18:19], v[16:17], v[34:35] op_sel_hi:[1,0]
	v_cvt_pk_bf16_f32 v16, v20, v21
	v_cvt_pk_bf16_f32 v17, v22, v23
	s_nop 0
	v_cvt_pk_bf16_f32 v18, v18, v19
	v_cvt_pk_bf16_f32 v19, v24, v25
	global_store_dwordx4 v[36:37], v[16:19], off offset:256 nt
	s_cbranch_vccnz .LBB0_872
	ds_read2st64_b32 v[16:17], v80 offset0:2 offset1:6
	s_waitcnt lgkmcnt(0)
	v_add_f32_e32 v16, v16, v17
	v_fmamk_f32 v16, v16, 0x3a000000, v158
	v_mul_f32_e32 v17, 0x4b800000, v16
	v_cmp_gt_f32_e32 vcc, s51, v16
	s_nop 1
	v_cndmask_b32_e32 v16, v16, v17, vcc
	v_rsq_f32_e32 v16, v16
	s_nop 0
	v_mul_f32_e32 v17, 0x45800000, v16
	v_cndmask_b32_e32 v32, v16, v17, vcc
.LBB0_872:
	s_nop 0
	v_add_u32_e32 v16, 0xb0, v159
	v_mad_i64_i32 v[16:17], s[14:15], v16, s86, 0
	v_lshl_add_u64 v[16:17], v[16:17], 1, v[144:145]
	v_pk_mul_f32 v[14:15], v[14:15], v[32:33] op_sel_hi:[1,0]
	v_pk_mul_f32 v[12:13], v[12:13], v[32:33] op_sel_hi:[1,0]
	v_pk_mul_f32 v[18:19], v[10:11], v[32:33] op_sel_hi:[1,0]
	v_pk_mul_f32 v[10:11], v[8:9], v[32:33] op_sel_hi:[1,0]
	v_cvt_pk_bf16_f32 v8, v12, v13
	v_cvt_pk_bf16_f32 v9, v14, v15
	s_and_b64 vcc, exec, s[38:39]
	v_cvt_pk_bf16_f32 v10, v10, v11
	v_cvt_pk_bf16_f32 v11, v18, v19
	global_store_dwordx4 v[16:17], v[8:11], off nt
	s_mov_b64 s[14:15], -1
	v_pk_mul_f32 v[6:7], v[6:7], v[32:33] op_sel_hi:[1,0]
	v_pk_mul_f32 v[8:9], v[2:3], v[32:33] op_sel_hi:[1,0]
	v_pk_mul_f32 v[2:3], v[0:1], v[32:33] op_sel_hi:[1,0]
	v_pk_mul_f32 v[4:5], v[4:5], v[32:33] op_sel_hi:[1,0]
	v_cvt_pk_bf16_f32 v1, v6, v7
	v_cvt_pk_bf16_f32 v2, v2, v3
	v_cvt_pk_bf16_f32 v3, v8, v9
	s_nop 0
	v_cvt_pk_bf16_f32 v0, v4, v5
	global_store_dwordx4 v[16:17], v[0:3], off offset:256 nt
	s_cbranch_vccnz .LBB0_846
	s_and_b64 vcc, exec, s[12:13]
	s_cbranch_vccz .LBB0_845
	v_lshl_or_b32 v0, s72, 8, v147
	v_ashrrev_i32_e32 v1, 31, v0
	v_lshlrev_b64 v[0:1], 7, v[0:1]
	v_lshl_add_u64 v[0:1], v[136:137], 0, v[0:1]
	s_and_b64 vcc, exec, s[42:43]
	s_cbranch_vccz .LBB0_878
	v_mov_b32_e32 v2, 0
	s_and_saveexec_b64 s[14:15], s[36:37]
	s_cbranch_execz .LBB0_877
	global_load_dword v2, v[0:1], off

; #define LAS __attribute__((address_space(3)))
; DEVI unsigned pk_bf16(float lo, float hi) { unsigned r; asm("v_cvt_pk_bf16_f32 %0, %1, %2" : "=v"(r) : "v"(lo), "v"(hi)); return r; }
; DEVI float row_rstd(const LAS float* rsl, int r) { return rsqrtf((rsl[r] + rsl[256 + r]) * (1.0f / DM) + 1e-6f); }
;     DEVI void operator()(const f32x4 (&acc)[2][2][4][2], const Unit& u, int wr, int wc, int fr, int fq, const LAS float* rsl) const {
;         bf16_t* const O = O_; const int ldc = ldc_; const float* const rs = rs_; const int rsn = rsn_;
;         const int row0 = u.pm * BM + wr * 64 + fr, col0 = u.pn * BM + wc * 32 + 8 * fq;
; #pragma unroll
;         for (int ai = 0; ai < 2; ++ai)
; #pragma unroll
;             for (int m = 0; m < 4; ++m) { bf16_t* rowp = O + (size_t)(row0 + ai * HALF + m * 16) * ldc + col0;
;                 const float sc = rs ? row_rstd(rsl, wr * 64 + fr + ai * HALF + m * 16) : 1.0f;
; #pragma unroll
;                 for (int bj = 0; bj < 2; ++bj) { const f32x4 v0 = acc[ai][bj][m][0] * sc, v1 = acc[ai][bj][m][1] * sc;
;                     u32x4 w; w.x = pk_bf16(v0[0], v0[1]); w.y = pk_bf16(v0[2], v0[3]); w.z = pk_bf16(v1[0], v1[1]); w.w = pk_bf16(v1[2], v1[3]);
;                     *(u32x4*)(rowp + bj * HALF) = w; } }
;     }
.LBB0_1983:
	v_lshl_or_b32 v144, s65, 8, v152
	v_readlane_b32 s14, v241, 8
	v_readlane_b32 s84, v241, 10
	v_lshl_add_u32 v159, s66, 8, v149
	v_ashrrev_i32_e32 v145, 31, v144
	v_readlane_b32 s15, v241, 9
	v_readlane_b32 s86, v241, 12
	v_pk_mul_f32 v[126:127], v[126:127], v[148:149] op_sel_hi:[1,0]
	v_lshl_add_u64 v[144:145], v[144:145], 1, s[14:15]
	v_mad_i64_i32 v[162:163], s[14:15], v159, s86, 0
	v_lshl_add_u64 v[162:163], v[162:163], 1, v[144:145]
	v_pk_mul_f32 v[124:125], v[124:125], v[148:149] op_sel_hi:[1,0]
	v_pk_mul_f32 v[164:165], v[122:123], v[148:149] op_sel_hi:[1,0]
	v_pk_mul_f32 v[122:123], v[120:121], v[148:149] op_sel_hi:[1,0]
	v_cvt_pk_bf16_f32 v120, v124, v125
	v_cvt_pk_bf16_f32 v121, v126, v127
	v_pk_mul_f32 v[116:117], v[116:117], v[148:149] op_sel_hi:[1,0]
	v_cvt_pk_bf16_f32 v122, v122, v123
	v_cvt_pk_bf16_f32 v123, v164, v165
	global_store_dwordx4 v[162:163], v[120:123], off nt
	v_pk_mul_f32 v[118:119], v[118:119], v[148:149] op_sel_hi:[1,0]
	s_and_b64 vcc, exec, s[38:39]
	v_pk_mul_f32 v[120:121], v[114:115], v[148:149] op_sel_hi:[1,0]
	v_pk_mul_f32 v[114:115], v[112:113], v[148:149] op_sel_hi:[1,0]
	v_cvt_pk_bf16_f32 v112, v116, v117
	v_cvt_pk_bf16_f32 v113, v118, v119
	v_readlane_b32 s85, v241, 11
	v_cvt_pk_bf16_f32 v114, v114, v115
	v_cvt_pk_bf16_f32 v115, v120, v121
	global_store_dwordx4 v[162:163], v[112:115], off offset:256 nt
	v_readlane_b32 s87, v241, 13
	s_nop 0
	v_add_u32_e32 v112, 64, v160
	s_cbranch_vccnz .LBB0_1985
	ds_read2st64_b32 v[114:115], v112 offset1:4
	s_waitcnt lgkmcnt(0)
	v_add_f32_e32 v113, v114, v115
	v_fmamk_f32 v113, v113, 0x3a000000, v158
	v_mul_f32_e32 v114, 0x4b800000, v113
	v_cmp_gt_f32_e32 vcc, s51, v113
	s_nop 1
	v_cndmask_b32_e32 v113, v113, v114, vcc
	v_rsq_f32_e32 v113, v113
	s_nop 0
	v_mul_f32_e32 v114, 0x45800000, v113
	v_cndmask_b32_e32 v146, v113, v114, vcc
.LBB0_1985:
	v_readlane_b32 s84, v241, 10
	v_or_b32_e32 v113, 16, v159
	v_readlane_b32 s86, v241, 12
	v_pk_mul_f32 v[110:111], v[110:111], v[146:147] op_sel_hi:[1,0]
	v_pk_mul_f32 v[108:109], v[108:109], v[146:147] op_sel_hi:[1,0]
	v_mad_i64_i32 v[114:115], s[14:15], v113, s86, 0
	v_lshl_add_u64 v[114:115], v[114:115], 1, v[144:145]
	v_pk_mul_f32 v[116:117], v[106:107], v[146:147] op_sel_hi:[1,0]
	v_pk_mul_f32 v[106:107], v[104:105], v[146:147] op_sel_hi:[1,0]
	v_cvt_pk_bf16_f32 v104, v108, v109
	v_cvt_pk_bf16_f32 v105, v110, v111
	v_pk_mul_f32 v[102:103], v[102:103], v[146:147] op_sel_hi:[1,0]
	v_cvt_pk_bf16_f32 v106, v106, v107
	v_cvt_pk_bf16_f32 v107, v116, v117
	global_store_dwordx4 v[114:115], v[104:107], off nt
	v_pk_mul_f32 v[100:101], v[100:101], v[146:147] op_sel_hi:[1,0]
	s_and_b64 vcc, exec, s[38:39]
	v_pk_mul_f32 v[104:105], v[98:99], v[146:147] op_sel_hi:[1,0]
	v_pk_mul_f32 v[98:99], v[96:97], v[146:147] op_sel_hi:[1,0]
	v_cvt_pk_bf16_f32 v96, v100, v101
	v_cvt_pk_bf16_f32 v97, v102, v103
	v_readlane_b32 s85, v241, 11
	v_cvt_pk_bf16_f32 v98, v98, v99
	v_cvt_pk_bf16_f32 v99, v104, v105
	global_store_dwordx4 v[114:115], v[96:99], off offset:256 nt
	v_readlane_b32 s87, v241, 13
	s_nop 0
	v_mov_b32_e32 v96, 1.0
	v_add_u32_e32 v97, 0x80, v160
	v_mov_b32_e32 v98, 1.0
	s_cbranch_vccnz .LBB0_1987
	ds_read2st64_b32 v[98:99], v97 offset1:4
	s_waitcnt lgkmcnt(0)
	v_add_f32_e32 v98, v98, v99
	v_fmamk_f32 v98, v98, 0x3a000000, v158
	v_mul_f32_e32 v99, 0x4b800000, v98
	v_cmp_gt_f32_e32 vcc, s51, v98
	s_nop 1
	v_cndmask_b32_e32 v98, v98, v99, vcc
	v_rsq_f32_e32 v98, v98
	s_nop 0
	v_mul_f32_e32 v99, 0x45800000, v98
	v_cndmask_b32_e32 v98, v98, v99, vcc
.LBB0_1987:
	v_readlane_b32 s84, v241, 10
	v_or_b32_e32 v99, 32, v159
	v_readlane_b32 s86, v241, 12
	v_pk_mul_f32 v[94:95], v[94:95], v[98:99] op_sel_hi:[1,0]
	v_pk_mul_f32 v[92:93], v[92:93], v[98:99] op_sel_hi:[1,0]
	v_mad_i64_i32 v[100:101], s[14:15], v99, s86, 0
	v_lshl_add_u64 v[100:101], v[100:101], 1, v[144:145]
	v_pk_mul_f32 v[102:103], v[90:91], v[98:99] op_sel_hi:[1,0]
	v_pk_mul_f32 v[90:91], v[88:89], v[98:99] op_sel_hi:[1,0]
	v_cvt_pk_bf16_f32 v88, v92, v93
	v_cvt_pk_bf16_f32 v89, v94, v95
	v_pk_mul_f32 v[84:85], v[84:85], v[98:99] op_sel_hi:[1,0]
	v_cvt_pk_bf16_f32 v90, v90, v91
	v_cvt_pk_bf16_f32 v91, v102, v103
	global_store_dwordx4 v[100:101], v[88:91], off nt
	v_pk_mul_f32 v[86:87], v[86:87], v[98:99] op_sel_hi:[1,0]
	s_and_b64 vcc, exec, s[38:39]
	v_pk_mul_f32 v[88:89], v[82:83], v[98:99] op_sel_hi:[1,0]
	v_pk_mul_f32 v[82:83], v[80:81], v[98:99] op_sel_hi:[1,0]
	v_cvt_pk_bf16_f32 v80, v84, v85
	v_cvt_pk_bf16_f32 v81, v86, v87
	v_readlane_b32 s85, v241, 11
	v_cvt_pk_bf16_f32 v82, v82, v83
	v_cvt_pk_bf16_f32 v83, v88, v89
	global_store_dwordx4 v[100:101], v[80:83], off offset:256 nt
	v_readlane_b32 s87, v241, 13
	s_nop 0
	v_add_u32_e32 v80, 0xc0, v160
	s_cbranch_vccnz .LBB0_1989
	ds_read2st64_b32 v[82:83], v80 offset1:4
	s_waitcnt lgkmcnt(0)
	v_add_f32_e32 v81, v82, v83
	v_fmamk_f32 v81, v81, 0x3a000000, v158
	v_mul_f32_e32 v82, 0x4b800000, v81
	v_cmp_gt_f32_e32 vcc, s51, v81
	s_nop 1
	v_cndmask_b32_e32 v81, v81, v82, vcc
	v_rsq_f32_e32 v81, v81
	s_nop 0
	v_mul_f32_e32 v82, 0x45800000, v81
	v_cndmask_b32_e32 v96, v81, v82, vcc
; #define LAS __attribute__((address_space(3)))
; DEVI unsigned pk_bf16(float lo, float hi) { unsigned r; asm("v_cvt_pk_bf16_f32 %0, %1, %2" : "=v"(r) : "v"(lo), "v"(hi)); return r; }
; DEVI float row_rstd(const LAS float* rsl, int r) { return rsqrtf((rsl[r] + rsl[256 + r]) * (1.0f / DM) + 1e-6f); }
;     DEVI void operator()(const f32x4 (&acc)[2][2][4][2], const Unit& u, int wr, int wc, int fr, int fq, const LAS float* rsl) const {
;         bf16_t* const O = O_; const int ldc = ldc_; const float* const rs = rs_; const int rsn = rsn_;
;         const int row0 = u.pm * BM + wr * 64 + fr, col0 = u.pn * BM + wc * 32 + 8 * fq;
; #pragma unroll
;         for (int ai = 0; ai < 2; ++ai)
; #pragma unroll
;             for (int m = 0; m < 4; ++m) { bf16_t* rowp = O + (size_t)(row0 + ai * HALF + m * 16) * ldc + col0;
;                 const float sc = rs ? row_rstd(rsl, wr * 64 + fr + ai * HALF + m * 16) : 1.0f;
; #pragma unroll
;                 for (int bj = 0; bj < 2; ++bj) { const f32x4 v0 = acc[ai][bj][m][0] * sc, v1 = acc[ai][bj][m][1] * sc;
;                     u32x4 w; w.x = pk_bf16(v0[0], v0[1]); w.y = pk_bf16(v0[2], v0[3]); w.z = pk_bf16(v1[0], v1[1]); w.w = pk_bf16(v1[2], v1[3]);
;                     *(u32x4*)(rowp + bj * HALF) = w; } }
;     }
.LBB0_1989:
	v_readlane_b32 s84, v241, 10
	v_or_b32_e32 v81, 48, v159
	v_readlane_b32 s86, v241, 12
	v_pk_mul_f32 v[78:79], v[78:79], v[96:97] op_sel_hi:[1,0]
	v_pk_mul_f32 v[76:77], v[76:77], v[96:97] op_sel_hi:[1,0]
	v_mad_i64_i32 v[82:83], s[14:15], v81, s86, 0
	v_lshl_add_u64 v[82:83], v[82:83], 1, v[144:145]
	v_pk_mul_f32 v[84:85], v[74:75], v[96:97] op_sel_hi:[1,0]
	v_pk_mul_f32 v[74:75], v[72:73], v[96:97] op_sel_hi:[1,0]
	v_cvt_pk_bf16_f32 v72, v76, v77
	v_cvt_pk_bf16_f32 v73, v78, v79
	v_pk_mul_f32 v[68:69], v[68:69], v[96:97] op_sel_hi:[1,0]
	v_cvt_pk_bf16_f32 v74, v74, v75
	v_cvt_pk_bf16_f32 v75, v84, v85
	global_store_dwordx4 v[82:83], v[72:75], off nt
	v_pk_mul_f32 v[70:71], v[70:71], v[96:97] op_sel_hi:[1,0]
	s_and_b64 vcc, exec, s[38:39]
	v_pk_mul_f32 v[72:73], v[66:67], v[96:97] op_sel_hi:[1,0]
	v_pk_mul_f32 v[66:67], v[64:65], v[96:97] op_sel_hi:[1,0]
	v_cvt_pk_bf16_f32 v64, v68, v69
	v_cvt_pk_bf16_f32 v65, v70, v71
	v_readlane_b32 s85, v241, 11
	v_cvt_pk_bf16_f32 v66, v66, v67
	v_cvt_pk_bf16_f32 v67, v72, v73
	global_store_dwordx4 v[82:83], v[64:67], off offset:256 nt
	v_readlane_b32 s87, v241, 13
	s_nop 0
	v_mov_b32_e32 v64, 1.0
	v_mov_b32_e32 v66, 1.0
	s_cbranch_vccnz .LBB0_1991
	ds_read2st64_b32 v[66:67], v160 offset0:2 offset1:6
	s_waitcnt lgkmcnt(0)
	v_add_f32_e32 v65, v66, v67
	v_fmamk_f32 v65, v65, 0x3a000000, v158
	v_mul_f32_e32 v66, 0x4b800000, v65
	v_cmp_gt_f32_e32 vcc, s51, v65
	s_nop 1
	v_cndmask_b32_e32 v65, v65, v66, vcc
	v_rsq_f32_e32 v65, v65
	s_nop 0
	v_mul_f32_e32 v66, 0x45800000, v65
	v_cndmask_b32_e32 v66, v65, v66, vcc
.LBB0_1991:
	v_readlane_b32 s84, v241, 10
	v_add_u32_e32 v65, 0x80, v159
	v_readlane_b32 s86, v241, 12
	v_pk_mul_f32 v[62:63], v[62:63], v[66:67] op_sel_hi:[1,0]
	v_pk_mul_f32 v[60:61], v[60:61], v[66:67] op_sel_hi:[1,0]
	v_mad_i64_i32 v[68:69], s[14:15], v65, s86, 0
	v_lshl_add_u64 v[68:69], v[68:69], 1, v[144:145]
	v_pk_mul_f32 v[70:71], v[58:59], v[66:67] op_sel_hi:[1,0]
	v_pk_mul_f32 v[58:59], v[56:57], v[66:67] op_sel_hi:[1,0]
	v_cvt_pk_bf16_f32 v56, v60, v61
	v_cvt_pk_bf16_f32 v57, v62, v63
	s_and_b64 vcc, exec, s[38:39]
	v_cvt_pk_bf16_f32 v58, v58, v59
	v_cvt_pk_bf16_f32 v59, v70, v71
	global_store_dwordx4 v[68:69], v[56:59], off nt
	v_readlane_b32 s85, v241, 11
	v_readlane_b32 s87, v241, 13
	v_pk_mul_f32 v[56:57], v[50:51], v[66:67] op_sel_hi:[1,0]
	v_pk_mul_f32 v[50:51], v[48:49], v[66:67] op_sel_hi:[1,0]
	v_pk_mul_f32 v[54:55], v[54:55], v[66:67] op_sel_hi:[1,0]
	v_pk_mul_f32 v[52:53], v[52:53], v[66:67] op_sel_hi:[1,0]
	v_cvt_pk_bf16_f32 v49, v54, v55
	v_cvt_pk_bf16_f32 v50, v50, v51
	v_cvt_pk_bf16_f32 v51, v56, v57
	s_nop 0
	v_cvt_pk_bf16_f32 v48, v52, v53
	global_store_dwordx4 v[68:69], v[48:51], off offset:256 nt
	s_cbranch_vccnz .LBB0_1993
	ds_read2st64_b32 v[48:49], v112 offset0:2 offset1:6
	s_waitcnt lgkmcnt(0)
	v_add_f32_e32 v48, v48, v49
	v_fmamk_f32 v48, v48, 0x3a000000, v158
	v_mul_f32_e32 v49, 0x4b800000, v48
	v_cmp_gt_f32_e32 vcc, s51, v48
	s_nop 1
	v_cndmask_b32_e32 v48, v48, v49, vcc
	v_rsq_f32_e32 v48, v48
	s_nop 0
	v_mul_f32_e32 v49, 0x45800000, v48
	v_cndmask_b32_e32 v64, v48, v49, vcc
; #define LAS __attribute__((address_space(3)))
; DEVI unsigned pk_bf16(float lo, float hi) { unsigned r; asm("v_cvt_pk_bf16_f32 %0, %1, %2" : "=v"(r) : "v"(lo), "v"(hi)); return r; }
; DEVI float row_rstd(const LAS float* rsl, int r) { return rsqrtf((rsl[r] + rsl[256 + r]) * (1.0f / DM) + 1e-6f); }
;     DEVI void operator()(const f32x4 (&acc)[2][2][4][2], const Unit& u, int wr, int wc, int fr, int fq, const LAS float* rsl) const {
;         bf16_t* const O = O_; const int ldc = ldc_; const float* const rs = rs_; const int rsn = rsn_;
;         const int row0 = u.pm * BM + wr * 64 + fr, col0 = u.pn * BM + wc * 32 + 8 * fq;
; #pragma unroll
;         for (int ai = 0; ai < 2; ++ai)
; #pragma unroll
;             for (int m = 0; m < 4; ++m) { bf16_t* rowp = O + (size_t)(row0 + ai * HALF + m * 16) * ldc + col0;
;                 const float sc = rs ? row_rstd(rsl, wr * 64 + fr + ai * HALF + m * 16) : 1.0f;
; #pragma unroll
;                 for (int bj = 0; bj < 2; ++bj) { const f32x4 v0 = acc[ai][bj][m][0] * sc, v1 = acc[ai][bj][m][1] * sc;
;                     u32x4 w; w.x = pk_bf16(v0[0], v0[1]); w.y = pk_bf16(v0[2], v0[3]); w.z = pk_bf16(v1[0], v1[1]); w.w = pk_bf16(v1[2], v1[3]);
;                     *(u32x4*)(rowp + bj * HALF) = w; } }
;     }
; template <class Epi>
; DEVI void gemm_phase(LAS unsigned char* lds, const bf16_t* gA, const bf16_t* gBt, const int lda, const int ldb, const int K, const StaticOrder S_, const Epi E) {
;     ...
;         if (!has_next) break;
; #pragma unroll
;         for (int a = 0; a < 2; ++a)
; #pragma unroll
;             for (int b = 0; b < 2; ++b)
; #pragma unroll
;                 for (int m = 0; m < 4; ++m)
; #pragma unroll
;                     for (int n = 0; n < 2; ++n) acc[a][b][m][n] = (f32x4){0.f, 0.f, 0.f, 0.f};
;         cur = nxt; cA = nA; cB = nB; ++ui;
;         rs_prefetch(cur, ui & 1);
.LBB0_1993:
	v_readlane_b32 s84, v241, 10
	v_add_u32_e32 v48, 0x90, v159
	v_readlane_b32 s86, v241, 12
	v_pk_mul_f32 v[46:47], v[46:47], v[64:65] op_sel_hi:[1,0]
	v_pk_mul_f32 v[44:45], v[44:45], v[64:65] op_sel_hi:[1,0]
	v_mad_i64_i32 v[48:49], s[14:15], v48, s86, 0
	v_lshl_add_u64 v[48:49], v[48:49], 1, v[144:145]
	v_pk_mul_f32 v[50:51], v[42:43], v[64:65] op_sel_hi:[1,0]
	v_pk_mul_f32 v[42:43], v[40:41], v[64:65] op_sel_hi:[1,0]
	v_cvt_pk_bf16_f32 v40, v44, v45
	v_cvt_pk_bf16_f32 v41, v46, v47
	v_pk_mul_f32 v[36:37], v[36:37], v[64:65] op_sel_hi:[1,0]
	v_cvt_pk_bf16_f32 v42, v42, v43
	v_cvt_pk_bf16_f32 v43, v50, v51
	global_store_dwordx4 v[48:49], v[40:43], off nt
	v_pk_mul_f32 v[38:39], v[38:39], v[64:65] op_sel_hi:[1,0]
	s_and_b64 vcc, exec, s[38:39]
	v_pk_mul_f32 v[40:41], v[34:35], v[64:65] op_sel_hi:[1,0]
	v_pk_mul_f32 v[34:35], v[32:33], v[64:65] op_sel_hi:[1,0]
	v_cvt_pk_bf16_f32 v32, v36, v37
	v_cvt_pk_bf16_f32 v33, v38, v39
	v_readlane_b32 s85, v241, 11
	v_cvt_pk_bf16_f32 v34, v34, v35
	v_cvt_pk_bf16_f32 v35, v40, v41
	global_store_dwordx4 v[48:49], v[32:35], off offset:256 nt
	v_readlane_b32 s87, v241, 13
	s_nop 0
	v_mov_b32_e32 v32, 1.0
	v_mov_b32_e32 v34, 1.0
	s_cbranch_vccnz .LBB0_1995
	ds_read2st64_b32 v[34:35], v97 offset0:2 offset1:6
	s_waitcnt lgkmcnt(0)
	v_add_f32_e32 v33, v34, v35
	v_fmamk_f32 v33, v33, 0x3a000000, v158
	v_mul_f32_e32 v34, 0x4b800000, v33
	v_cmp_gt_f32_e32 vcc, s51, v33
	s_nop 1
	v_cndmask_b32_e32 v33, v33, v34, vcc
	v_rsq_f32_e32 v33, v33
	s_nop 0
	v_mul_f32_e32 v34, 0x45800000, v33
	v_cndmask_b32_e32 v34, v33, v34, vcc
.LBB0_1995:
	v_readlane_b32 s84, v241, 10
	v_add_u32_e32 v33, 0xa0, v159
	v_readlane_b32 s86, v241, 12
	v_pk_mul_f32 v[30:31], v[30:31], v[34:35] op_sel_hi:[1,0]
	v_pk_mul_f32 v[28:29], v[28:29], v[34:35] op_sel_hi:[1,0]
	v_mad_i64_i32 v[36:37], s[14:15], v33, s86, 0
	v_lshl_add_u64 v[36:37], v[36:37], 1, v[144:145]
	v_pk_mul_f32 v[38:39], v[26:27], v[34:35] op_sel_hi:[1,0]
	v_pk_mul_f32 v[26:27], v[24:25], v[34:35] op_sel_hi:[1,0]
	v_cvt_pk_bf16_f32 v24, v28, v29
	v_cvt_pk_bf16_f32 v25, v30, v31
	s_and_b64 vcc, exec, s[38:39]
	v_cvt_pk_bf16_f32 v26, v26, v27
	v_cvt_pk_bf16_f32 v27, v38, v39
	global_store_dwordx4 v[36:37], v[24:27], off nt
	v_readlane_b32 s85, v241, 11
	v_readlane_b32 s87, v241, 13
	v_pk_mul_f32 v[24:25], v[18:19], v[34:35] op_sel_hi:[1,0]
	v_pk_mul_f32 v[18:19], v[16:17], v[34:35] op_sel_hi:[1,0]
	v_pk_mul_f32 v[22:23], v[22:23], v[34:35] op_sel_hi:[1,0]
	v_pk_mul_f32 v[20:21], v[20:21], v[34:35] op_sel_hi:[1,0]
	v_cvt_pk_bf16_f32 v17, v22, v23
	v_cvt_pk_bf16_f32 v18, v18, v19
	v_cvt_pk_bf16_f32 v19, v24, v25
	s_nop 0
	v_cvt_pk_bf16_f32 v16, v20, v21
	global_store_dwordx4 v[36:37], v[16:19], off offset:256 nt
	s_cbranch_vccnz .LBB0_1997
	ds_read2st64_b32 v[16:17], v80 offset0:2 offset1:6
	s_waitcnt lgkmcnt(0)
	v_add_f32_e32 v16, v16, v17
	v_fmamk_f32 v16, v16, 0x3a000000, v158
	v_mul_f32_e32 v17, 0x4b800000, v16
	v_cmp_gt_f32_e32 vcc, s51, v16
	s_nop 1
	v_cndmask_b32_e32 v16, v16, v17, vcc
	v_rsq_f32_e32 v16, v16
	s_nop 0
	v_mul_f32_e32 v17, 0x45800000, v16
	v_cndmask_b32_e32 v32, v16, v17, vcc
.LBB0_1997:
	v_readlane_b32 s84, v241, 10
	v_add_u32_e32 v16, 0xb0, v159
	v_readlane_b32 s86, v241, 12
	v_pk_mul_f32 v[14:15], v[14:15], v[32:33] op_sel_hi:[1,0]
	v_pk_mul_f32 v[12:13], v[12:13], v[32:33] op_sel_hi:[1,0]
	v_mad_i64_i32 v[16:17], s[14:15], v16, s86, 0
	v_lshl_add_u64 v[16:17], v[16:17], 1, v[144:145]
	v_pk_mul_f32 v[18:19], v[10:11], v[32:33] op_sel_hi:[1,0]
	v_pk_mul_f32 v[10:11], v[8:9], v[32:33] op_sel_hi:[1,0]
	v_cvt_pk_bf16_f32 v8, v12, v13
	v_cvt_pk_bf16_f32 v9, v14, v15
	s_and_b64 vcc, exec, s[36:37]
	v_cvt_pk_bf16_f32 v10, v10, v11
	v_cvt_pk_bf16_f32 v11, v18, v19
	global_store_dwordx4 v[16:17], v[8:11], off nt
	s_mov_b64 s[14:15], -1
	v_readlane_b32 s85, v241, 11
	v_pk_mul_f32 v[8:9], v[2:3], v[32:33] op_sel_hi:[1,0]
	v_pk_mul_f32 v[2:3], v[0:1], v[32:33] op_sel_hi:[1,0]
	v_readlane_b32 s87, v241, 13
	v_pk_mul_f32 v[6:7], v[6:7], v[32:33] op_sel_hi:[1,0]
	v_pk_mul_f32 v[4:5], v[4:5], v[32:33] op_sel_hi:[1,0]
	v_cvt_pk_bf16_f32 v1, v6, v7
	v_cvt_pk_bf16_f32 v2, v2, v3
	v_cvt_pk_bf16_f32 v3, v8, v9
	s_nop 0
	v_cvt_pk_bf16_f32 v0, v4, v5
	global_store_dwordx4 v[16:17], v[0:3], off offset:256 nt
	s_cbranch_vccnz .LBB0_1971
	s_and_b64 vcc, exec, s[12:13]
	s_cbranch_vccz .LBB0_1970
	v_lshl_or_b32 v0, s64, 8, v147
	v_ashrrev_i32_e32 v1, 31, v0
	v_lshlrev_b64 v[0:1], 7, v[0:1]
	v_lshl_add_u64 v[0:1], v[136:137], 0, v[0:1]
	s_and_b64 vcc, exec, s[40:41]
	s_cbranch_vccz .LBB0_2003
	v_mov_b32_e32 v2, 0
	s_and_saveexec_b64 s[14:15], s[34:35]
	s_cbranch_execz .LBB0_2002
	global_load_dword v2, v[0:1], off
